# gdn_prep stage A: second chunk's row loads prefetched into a second register set during the first chunk's pass (on top of v14)
# speedup vs baseline: 1.0060x; 1.0012x over previous
; template <int STRIP> __device__ __forceinline__ void ph_gdn_prep_fast(const bf16* __restrict__ proj, const float* __restrict__ small, const float* __restrict__ conv_w, const float* __restrict__ a_log, const float* __restrict__ dt_bias, ...
;     ...
;             for (int cs = 0; cs < 2; ++cs) {
;                 const int n = 2 * (pair & 31) + cs; const size_t m0 = (size_t)b * SEQ + n * 64;
;                 unsigned char* L = lds_dyn + cs * GP_CHUNK;
;                 const int tb = n * 64 + 4 * ts - 3;
;                 u32x2 xr[3][7];
; #pragma unroll
;                 for (int which = 0; which < 3; ++which)
; #pragma unroll
;                     for (int r = 0; r < 7; ++r) { const bool ok = tb + r >= 0; const bf16* src = proj + (m0 + 4 * ts - (ok ? 3 - r : 0)) * NPROJ + which * 768 + h * 128 + 4 * cg;
;                         xr[which][r] = *(const u32x2*)src; if (!ok) xr[which][r] = (u32x2){0u, 0u}; }
.LBB0_1256:
	s_cmp_lg_u32 s2, 0
	s_cbranch_scc1 .Lsa_iter1
	v_cndmask_b32_e64 v2, 0, 1, s[0:1]
	v_cmp_ne_u32_e64 s[4:5], 1, v2
	v_or_b32_e32 v2, s2, v53
	v_lshlrev_b32_e32 v2, 6, v2
	v_add_u32_e32 v84, v2, v56
	v_cmp_lt_i32_e64 s[8:9], 2, v84
	v_lshl_add_u64 v[76:77], v[58:59], 0, v[2:3]
	v_cmp_lt_i32_e64 s[14:15], 1, v84
	v_cndmask_b32_e64 v63, 0, -1, s[8:9]
	v_cndmask_b32_e64 v62, 0, -3, s[8:9]
	v_lshl_add_u64 v[62:63], v[62:63], 0, v[76:77]
	v_mad_u64_u32 v[66:67], s[0:1], v62, s23, v[60:61]
	v_mad_i32_i24 v67, v63, s23, v67
	global_load_dwordx2 v[134:135], v[66:67], off
	v_cmp_lt_i32_e64 s[16:17], 0, v84
	v_mad_u64_u32 v[68:69], s[0:1], v76, s23, v[60:61]
	s_nop 0
	v_cndmask_b32_e64 v2, 0, 1, s[16:17]
	v_sub_co_u32_e32 v2, vcc, v76, v2
	v_mad_u64_u32 v[74:75], s[0:1], v2, s23, v[60:61]
	v_mad_i32_i24 v69, v77, s23, v69
	v_cmp_lt_i32_e64 s[10:11], -1, v84
	v_cmp_lt_i32_e64 s[6:7], -3, v84
	v_cmp_lt_i32_e64 s[12:13], -4, v84
	v_cndmask_b32_e64 v63, 0, -1, s[14:15]
	v_cndmask_b32_e64 v62, 0, -2, s[14:15]
	v_lshl_add_u64 v[62:63], v[62:63], 0, v[76:77]
	v_mad_u64_u32 v[70:71], s[0:1], v62, s23, v[60:61]
	v_mad_i32_i24 v71, v63, s23, v71
	global_load_dwordx2 v[136:137], v[70:71], off
	v_subbrev_co_u32_e32 v62, vcc, 0, v77, vcc
	v_mad_i32_i24 v75, v62, s23, v75
	global_load_dwordx2 v[138:139], v[74:75], off
	v_cmp_lt_i32_e32 vcc, -2, v84
	global_load_dwordx2 v[140:141], v[68:69], off
	s_nop 0
	v_cndmask_b32_e64 v2, 0, 1, vcc
	v_or_b32_e32 v2, v76, v2
	v_mad_u64_u32 v[62:63], s[0:1], v2, s23, v[60:61]
	v_mad_i32_i24 v63, v77, s23, v63
	global_load_dwordx2 v[142:143], v[62:63], off
	v_cndmask_b32_e64 v2, 0, 2, s[6:7]
	v_or_b32_e32 v2, v2, v76
	v_mad_u64_u32 v[64:65], s[0:1], v2, s23, v[60:61]
	v_mad_i32_i24 v65, v77, s23, v65
	global_load_dwordx2 v[144:145], v[64:65], off
	v_cndmask_b32_e64 v2, 0, 3, s[12:13]
	v_or_b32_e32 v2, v2, v76
	v_mad_u64_u32 v[72:73], s[0:1], v2, s23, v[60:61]
	v_mad_i32_i24 v73, v77, s23, v73
	global_load_dwordx2 v[146:147], v[72:73], off
	s_mul_i32 s0, s2, 0x11500
	v_add_u32_e32 v118, s0, v80
	s_mov_b32 s2, 1
	global_load_dwordx2 v[148:149], v[66:67], off offset:1536
	global_load_dwordx2 v[150:151], v[70:71], off offset:1536
	global_load_dwordx2 v[152:153], v[74:75], off offset:1536
	global_load_dwordx2 v[154:155], v[68:69], off offset:1536
	global_load_dwordx2 v[156:157], v[62:63], off offset:1536
	s_nop 0
	global_load_dwordx2 v[158:159], v[66:67], off offset:3072
	global_load_dwordx2 v[160:161], v[70:71], off offset:3072
	global_load_dwordx2 v[162:163], v[64:65], off offset:1536
	global_load_dwordx2 v[164:165], v[74:75], off offset:3072
	global_load_dwordx2 v[166:167], v[68:69], off offset:3072
	global_load_dwordx2 v[168:169], v[62:63], off offset:3072
	global_load_dwordx2 v[170:171], v[72:73], off offset:1536
	global_load_dwordx2 v[172:173], v[64:65], off offset:3072
	global_load_dwordx2 v[174:175], v[72:73], off offset:3072
	v_mov_b32_e32 v252, 0xc6400
	v_add_co_u32_e64 v228, s[100:101], v252, v68
	s_nop 1
	v_addc_co_u32_e64 v229, s[100:101], 0, v69, s[100:101]
	s_mov_b32 s100, 0x3400
	s_mov_b32 s101, 0
	v_lshl_add_u64 v[176:177], v[228:229], 0, s[100:101]
	v_lshl_add_u64 v[178:179], v[176:177], 0, s[100:101]
	v_lshl_add_u64 v[244:245], v[178:179], 0, s[100:101]
	v_lshl_add_u64 v[246:247], v[244:245], 0, s[100:101]
	v_lshl_add_u64 v[248:249], v[246:247], 0, s[100:101]
	v_lshl_add_u64 v[250:251], v[248:249], 0, s[100:101]
	global_load_dwordx2 v[186:187], v[228:229], off
	global_load_dwordx2 v[188:189], v[176:177], off
	global_load_dwordx2 v[190:191], v[178:179], off
	global_load_dwordx2 v[192:193], v[244:245], off
	global_load_dwordx2 v[194:195], v[246:247], off
	global_load_dwordx2 v[196:197], v[248:249], off
	global_load_dwordx2 v[198:199], v[250:251], off
	global_load_dwordx2 v[200:201], v[228:229], off offset:1536
	global_load_dwordx2 v[202:203], v[176:177], off offset:1536
	global_load_dwordx2 v[204:205], v[178:179], off offset:1536
	global_load_dwordx2 v[206:207], v[244:245], off offset:1536
	global_load_dwordx2 v[208:209], v[246:247], off offset:1536
	global_load_dwordx2 v[210:211], v[228:229], off offset:3072
	global_load_dwordx2 v[212:213], v[176:177], off offset:3072
	global_load_dwordx2 v[214:215], v[248:249], off offset:1536
	global_load_dwordx2 v[216:217], v[178:179], off offset:3072
	global_load_dwordx2 v[218:219], v[244:245], off offset:3072
	global_load_dwordx2 v[220:221], v[246:247], off offset:3072
	global_load_dwordx2 v[222:223], v[250:251], off offset:1536
	global_load_dwordx2 v[224:225], v[248:249], off offset:3072
	global_load_dwordx2 v[226:227], v[250:251], off offset:3072
	s_waitcnt vmcnt(21)
	v_cndmask_b32_e64 v119, 0, v134, s[8:9]
	v_cndmask_b32_e64 v122, 0, v135, s[8:9]
	v_cndmask_b32_e64 v120, 0, v136, s[14:15]
	v_cndmask_b32_e64 v124, 0, v137, s[14:15]
	v_cndmask_b32_e64 v121, 0, v138, s[16:17]
	v_cndmask_b32_e64 v125, 0, v139, s[16:17]
	v_cndmask_b32_e64 v87, 0, v140, s[10:11]
	v_cndmask_b32_e64 v123, 0, v141, s[10:11]
	v_cndmask_b32_e32 v116, 0, v142, vcc
	v_cndmask_b32_e32 v117, 0, v143, vcc
	v_cndmask_b32_e64 v113, 0, v144, s[6:7]
	v_cndmask_b32_e64 v115, 0, v145, s[6:7]
	v_cndmask_b32_e64 v2, 0, v146, s[12:13]
	v_cndmask_b32_e64 v114, 0, v147, s[12:13]
	v_cndmask_b32_e64 v106, 0, v148, s[8:9]
	v_cndmask_b32_e64 v110, 0, v149, s[8:9]
	v_cndmask_b32_e64 v107, 0, v150, s[14:15]
	v_cndmask_b32_e64 v111, 0, v151, s[14:15]
	v_cndmask_b32_e64 v108, 0, v152, s[16:17]
	v_cndmask_b32_e64 v112, 0, v153, s[16:17]
	v_cndmask_b32_e64 v105, 0, v154, s[10:11]
	v_cndmask_b32_e64 v109, 0, v155, s[10:11]
	v_cndmask_b32_e32 v103, 0, v156, vcc
	v_cndmask_b32_e32 v104, 0, v157, vcc
	v_cndmask_b32_e64 v88, 0, v158, s[8:9]
	v_cndmask_b32_e64 v95, 0, v159, s[8:9]
	v_cndmask_b32_e64 v89, 0, v160, s[14:15]
	v_cndmask_b32_e64 v96, 0, v161, s[14:15]
	v_cndmask_b32_e64 v94, 0, v164, s[16:17]
	v_cndmask_b32_e64 v98, 0, v165, s[16:17]
	v_and_b32_e32 v69, 0xffff0000, v124
	v_cndmask_b32_e64 v101, 0, v162, s[6:7]
	v_cndmask_b32_e64 v102, 0, v163, s[6:7]
	v_lshlrev_b32_e32 v68, 16, v124
	v_pk_mul_f32 v[70:71], v[6:7], v[68:69]
	v_cndmask_b32_e64 v91, 0, v166, s[10:11]
	v_cndmask_b32_e64 v97, 0, v167, s[10:11]
	v_cndmask_b32_e32 v92, 0, v168, vcc
	v_cndmask_b32_e32 v93, 0, v169, vcc
	v_and_b32_e32 v67, 0xffff0000, v122
	v_lshlrev_b32_e32 v66, 16, v122
	v_pk_fma_f32 v[66:67], v[14:15], v[66:67], v[70:71]
	v_and_b32_e32 v65, 0xffff0000, v123
	v_lshlrev_b32_e32 v64, 16, v123
	v_cndmask_b32_e64 v99, 0, v170, s[12:13]
	v_cndmask_b32_e64 v100, 0, v171, s[12:13]
	v_and_b32_e32 v77, 0xffff0000, v120
	v_and_b32_e32 v123, 0xffff0000, v119
	v_lshlrev_b32_e32 v122, 16, v119
	v_cndmask_b32_e64 v86, 0, v172, s[6:7]
	v_cndmask_b32_e64 v90, 0, v173, s[6:7]
	v_cndmask_b32_e64 v84, 0, v174, s[12:13]
	v_cndmask_b32_e64 v85, 0, v175, s[12:13]
	s_branch .Lsa_join
; __device__ __forceinline__ float bf2f(bf16 v) { return __uint_as_float(((unsigned)v) << 16); }
; __device__ __forceinline__ float siluf_(float x) { return x * sigmoidf_(x); }
; template <int STRIP> __device__ __forceinline__ void ph_gdn_prep_fast(const bf16* __restrict__ proj, const float* __restrict__ small, const float* __restrict__ conv_w, const float* __restrict__ a_log, const float* __restrict__ dt_bias, ...
;     ...
;                     for (int r = 0; r < 7; ++r) { const bool ok = tb + r >= 0; const bf16* src = proj + (m0 + 4 * ts - (ok ? 3 - r : 0)) * NPROJ + which * 768 + h * 128 + 4 * cg;
;                         xr[which][r] = *(const u32x2*)src; if (!ok) xr[which][r] = (u32x2){0u, 0u}; }
; #pragma unroll
;                 for (int which = 0; which < 3; ++which) {
;                     float xf[7][4];
; #pragma unroll
;                     for (int r = 0; r < 7; ++r) { xf[r][0] = bf2f((bf16)(xr[which][r].x & 0xffff)); xf[r][1] = bf2f((bf16)(xr[which][r].x >> 16)); xf[r][2] = bf2f((bf16)(xr[which][r].y & 0xffff)); xf[r][3] = bf2f((bf16)(xr[which][r].y >> 16)); }
; #pragma unroll
;                     for (int j = 0; j < 4; ++j) { float y[4]; float ss = 0.f;
; #pragma unroll
;                         for (int e = 0; e < 4; ++e) { float v = cw[which][0][e] * xf[j][e]; v += cw[which][1][e] * xf[j + 1][e]; v += cw[which][2][e] * xf[j + 2][e]; v += cw[which][3][e] * xf[j + 3][e]; y[e] = siluf_(v); ss += y[e] * y[e]; }
.Lsa_iter1:
	v_cndmask_b32_e64 v2, 0, 1, s[0:1]
	v_cmp_ne_u32_e64 s[4:5], 1, v2
	v_or_b32_e32 v2, s2, v53
	v_lshlrev_b32_e32 v2, 6, v2
	v_add_u32_e32 v84, v2, v56
	v_cmp_lt_i32_e64 s[8:9], 2, v84
	v_lshl_add_u64 v[76:77], v[58:59], 0, v[2:3]
	v_cmp_lt_i32_e64 s[14:15], 1, v84
	v_cndmask_b32_e64 v63, 0, -1, s[8:9]
	v_cndmask_b32_e64 v62, 0, -3, s[8:9]
	v_lshl_add_u64 v[62:63], v[62:63], 0, v[76:77]
	v_mad_u64_u32 v[66:67], s[0:1], v62, s23, v[60:61]
	v_mad_i32_i24 v67, v63, s23, v67
	v_cmp_lt_i32_e64 s[16:17], 0, v84
	v_mad_u64_u32 v[68:69], s[0:1], v76, s23, v[60:61]
	s_nop 0
	v_cndmask_b32_e64 v2, 0, 1, s[16:17]
	v_sub_co_u32_e32 v2, vcc, v76, v2
	v_mad_u64_u32 v[74:75], s[0:1], v2, s23, v[60:61]
	v_mad_i32_i24 v69, v77, s23, v69
	v_cmp_lt_i32_e64 s[10:11], -1, v84
	v_cmp_lt_i32_e64 s[6:7], -3, v84
	v_cmp_lt_i32_e64 s[12:13], -4, v84
	v_cndmask_b32_e64 v63, 0, -1, s[14:15]
	v_cndmask_b32_e64 v62, 0, -2, s[14:15]
	v_lshl_add_u64 v[62:63], v[62:63], 0, v[76:77]
	v_mad_u64_u32 v[70:71], s[0:1], v62, s23, v[60:61]
	v_mad_i32_i24 v71, v63, s23, v71
	v_subbrev_co_u32_e32 v62, vcc, 0, v77, vcc
	v_mad_i32_i24 v75, v62, s23, v75
	v_cmp_lt_i32_e32 vcc, -2, v84
	s_nop 0
	v_cndmask_b32_e64 v2, 0, 1, vcc
	v_or_b32_e32 v2, v76, v2
	v_mad_u64_u32 v[62:63], s[0:1], v2, s23, v[60:61]
	v_mad_i32_i24 v63, v77, s23, v63
	v_cndmask_b32_e64 v2, 0, 2, s[6:7]
	v_or_b32_e32 v2, v2, v76
	v_mad_u64_u32 v[64:65], s[0:1], v2, s23, v[60:61]
	v_mad_i32_i24 v65, v77, s23, v65
	v_cndmask_b32_e64 v2, 0, 3, s[12:13]
	v_or_b32_e32 v2, v2, v76
	v_mad_u64_u32 v[72:73], s[0:1], v2, s23, v[60:61]
	v_mad_i32_i24 v73, v77, s23, v73
	s_mul_i32 s0, s2, 0x11500
	v_add_u32_e32 v118, s0, v80
	s_mov_b32 s2, 1
	s_nop 0
	s_waitcnt vmcnt(0)
	v_cndmask_b32_e64 v119, 0, v186, s[8:9]
	v_cndmask_b32_e64 v122, 0, v187, s[8:9]
	v_cndmask_b32_e64 v120, 0, v188, s[14:15]
	v_cndmask_b32_e64 v124, 0, v189, s[14:15]
	v_cndmask_b32_e64 v121, 0, v190, s[16:17]
	v_cndmask_b32_e64 v125, 0, v191, s[16:17]
	v_cndmask_b32_e64 v87, 0, v192, s[10:11]
	v_cndmask_b32_e64 v123, 0, v193, s[10:11]
	v_cndmask_b32_e32 v116, 0, v194, vcc
	v_cndmask_b32_e32 v117, 0, v195, vcc
	v_cndmask_b32_e64 v113, 0, v196, s[6:7]
	v_cndmask_b32_e64 v115, 0, v197, s[6:7]
	v_cndmask_b32_e64 v2, 0, v198, s[12:13]
	v_cndmask_b32_e64 v114, 0, v199, s[12:13]
	v_cndmask_b32_e64 v106, 0, v200, s[8:9]
	v_cndmask_b32_e64 v110, 0, v201, s[8:9]
	v_cndmask_b32_e64 v107, 0, v202, s[14:15]
	v_cndmask_b32_e64 v111, 0, v203, s[14:15]
	v_cndmask_b32_e64 v108, 0, v204, s[16:17]
	v_cndmask_b32_e64 v112, 0, v205, s[16:17]
	v_cndmask_b32_e64 v105, 0, v206, s[10:11]
	v_cndmask_b32_e64 v109, 0, v207, s[10:11]
	v_cndmask_b32_e32 v103, 0, v208, vcc
	v_cndmask_b32_e32 v104, 0, v209, vcc
	v_cndmask_b32_e64 v88, 0, v210, s[8:9]
	v_cndmask_b32_e64 v95, 0, v211, s[8:9]
	v_cndmask_b32_e64 v89, 0, v212, s[14:15]
	v_cndmask_b32_e64 v96, 0, v213, s[14:15]
	v_cndmask_b32_e64 v94, 0, v216, s[16:17]
	v_cndmask_b32_e64 v98, 0, v217, s[16:17]
	v_and_b32_e32 v69, 0xffff0000, v124
	v_cndmask_b32_e64 v101, 0, v214, s[6:7]
	v_cndmask_b32_e64 v102, 0, v215, s[6:7]
	v_lshlrev_b32_e32 v68, 16, v124
	v_pk_mul_f32 v[70:71], v[6:7], v[68:69]
	v_cndmask_b32_e64 v91, 0, v218, s[10:11]
	v_cndmask_b32_e64 v97, 0, v219, s[10:11]
	v_cndmask_b32_e32 v92, 0, v220, vcc
	v_cndmask_b32_e32 v93, 0, v221, vcc
	v_and_b32_e32 v67, 0xffff0000, v122
	v_lshlrev_b32_e32 v66, 16, v122
	v_pk_fma_f32 v[66:67], v[14:15], v[66:67], v[70:71]
	v_and_b32_e32 v65, 0xffff0000, v123
	v_lshlrev_b32_e32 v64, 16, v123
	v_cndmask_b32_e64 v99, 0, v222, s[12:13]
	v_cndmask_b32_e64 v100, 0, v223, s[12:13]
	v_and_b32_e32 v77, 0xffff0000, v120
	v_and_b32_e32 v123, 0xffff0000, v119
	v_lshlrev_b32_e32 v122, 16, v119
	v_cndmask_b32_e64 v86, 0, v224, s[6:7]
	v_cndmask_b32_e64 v90, 0, v225, s[6:7]
	v_cndmask_b32_e64 v84, 0, v226, s[12:13]
	v_cndmask_b32_e64 v85, 0, v227, s[12:13]
.Lsa_join:
	v_and_b32_e32 v63, 0xffff0000, v125
	v_lshlrev_b32_e32 v62, 16, v125
	v_pk_fma_f32 v[66:67], v[10:11], v[62:63], v[66:67]
	s_nop 0
	v_pk_fma_f32 v[66:67], v[38:39], v[64:65], v[66:67]
	s_nop 0
	v_mul_f32_e32 v70, 0xbfb8aa3b, v66
	v_mul_f32_e32 v71, 0xbfb8aa3b, v67
	v_exp_f32_e32 v70, v70
	v_exp_f32_e32 v71, v71
	s_nop 0
	v_pk_add_f32 v[70:71], v[70:71], 1.0 op_sel_hi:[1,0]
	s_nop 0
	v_div_scale_f32 v72, s[0:1], v71, v71, 1.0
	v_rcp_f32_e32 v73, v72
	s_nop 0
	v_fma_f32 v74, -v72, v73, 1.0
	v_fmac_f32_e32 v73, v74, v73
	v_div_scale_f32 v74, vcc, 1.0, v71, 1.0
	v_mul_f32_e32 v75, v74, v73
	v_fma_f32 v76, -v72, v75, v74
	v_fmac_f32_e32 v75, v76, v73
	v_fma_f32 v72, -v72, v75, v74
	v_div_fmas_f32 v72, v72, v73, v75
	v_div_fixup_f32 v71, v72, v71, 1.0
	v_div_scale_f32 v72, s[0:1], v70, v70, 1.0
	v_rcp_f32_e32 v73, v72
	s_nop 0
	v_fma_f32 v74, -v72, v73, 1.0
	v_fmac_f32_e32 v73, v74, v73
	v_div_scale_f32 v74, vcc, 1.0, v70, 1.0
	v_mul_f32_e32 v75, v74, v73
	v_fma_f32 v76, -v72, v75, v74
	v_fmac_f32_e32 v75, v76, v73
	v_fma_f32 v72, -v72, v75, v74
	v_div_fmas_f32 v72, v72, v73, v75
	v_div_fixup_f32 v70, v72, v70, 1.0
	v_lshlrev_b32_e32 v76, 16, v120
	v_pk_mul_f32 v[70:71], v[66:67], v[70:71]
	v_and_b32_e32 v67, 0xffff0000, v121
	v_lshlrev_b32_e32 v66, 16, v121
	v_pk_mul_f32 v[120:121], v[4:5], v[76:77]
	v_and_b32_e32 v75, 0xffff0000, v87
	v_pk_fma_f32 v[120:121], v[12:13], v[122:123], v[120:121]
	v_lshlrev_b32_e32 v74, 16, v87
	v_pk_fma_f32 v[120:121], v[8:9], v[66:67], v[120:121]
	v_pk_mul_f32 v[72:73], v[70:71], v[70:71]
	v_pk_fma_f32 v[120:121], v[36:37], v[74:75], v[120:121]
	s_nop 0
	v_mul_f32_e32 v87, 0xbfb8aa3b, v120
	v_exp_f32_e32 v122, v87
	v_mul_f32_e32 v87, 0xbfb8aa3b, v121
	v_exp_f32_e32 v123, v87
	s_nop 0
; __device__ __forceinline__ float siluf_(float x) { return x * sigmoidf_(x); }
; template <int STRIP> __device__ __forceinline__ void ph_gdn_prep_fast(const bf16* __restrict__ proj, const float* __restrict__ small, const float* __restrict__ conv_w, const float* __restrict__ a_log, const float* __restrict__ dt_bias, ...
;     ...
;                     for (int j = 0; j < 4; ++j) { float y[4]; float ss = 0.f;
; #pragma unroll
;                         for (int e = 0; e < 4; ++e) { float v = cw[which][0][e] * xf[j][e]; v += cw[which][1][e] * xf[j + 1][e]; v += cw[which][2][e] * xf[j + 2][e]; v += cw[which][3][e] * xf[j + 3][e]; y[e] = siluf_(v); ss += y[e] * y[e]; }
;                         float r = 1.f;
;                         if (which < 2) { ss = row16_sum(ss); ss += __shfl_xor(ss, 16); r = rsqrtf(ss + NORM_EPS); if (which == 0) r *= 0.08838834764831845f; }
	v_pk_add_f32 v[122:123], v[122:123], 1.0 op_sel_hi:[1,0]
	s_nop 0
	v_div_scale_f32 v87, s[0:1], v123, v123, 1.0
	v_rcp_f32_e32 v119, v87
	s_nop 0
	v_fma_f32 v124, -v87, v119, 1.0
	v_fmac_f32_e32 v119, v124, v119
	v_div_scale_f32 v124, vcc, 1.0, v123, 1.0
	v_mul_f32_e32 v125, v124, v119
	v_fma_f32 v126, -v87, v125, v124
	v_fmac_f32_e32 v125, v126, v119
	v_fma_f32 v87, -v87, v125, v124
	v_div_fmas_f32 v87, v87, v119, v125
	v_div_fixup_f32 v123, v87, v123, 1.0
	v_div_scale_f32 v87, s[0:1], v122, v122, 1.0
	v_rcp_f32_e32 v119, v87
	s_nop 0
	v_fma_f32 v124, -v87, v119, 1.0
	v_fmac_f32_e32 v119, v124, v119
	v_div_scale_f32 v124, vcc, 1.0, v122, 1.0
	v_mul_f32_e32 v125, v124, v119
	v_fma_f32 v126, -v87, v125, v124
	v_fmac_f32_e32 v125, v126, v119
	v_pk_mul_f32 v[126:127], v[6:7], v[62:63]
	v_fma_f32 v87, -v87, v125, v124
	v_pk_fma_f32 v[68:69], v[14:15], v[68:69], v[126:127]
	v_div_fmas_f32 v87, v87, v119, v125
	v_and_b32_e32 v125, 0xffff0000, v117
	v_lshlrev_b32_e32 v124, 16, v117
	v_pk_fma_f32 v[68:69], v[10:11], v[64:65], v[68:69]
	v_div_fixup_f32 v122, v87, v122, 1.0
	v_pk_fma_f32 v[68:69], v[38:39], v[124:125], v[68:69]
	v_pk_mul_f32 v[120:121], v[120:121], v[122:123]
	v_mul_f32_e32 v117, 0xbfb8aa3b, v68
	v_exp_f32_e32 v126, v117
	v_mul_f32_e32 v117, 0xbfb8aa3b, v69
	v_exp_f32_e32 v127, v117
	v_pk_mul_f32 v[122:123], v[120:121], v[120:121]
	v_add_u32_e32 v87, v118, v82
	v_pk_add_f32 v[126:127], v[126:127], 1.0 op_sel_hi:[1,0]
	s_nop 0
	v_div_scale_f32 v117, s[0:1], v127, v127, 1.0
	v_rcp_f32_e32 v119, v117
	s_nop 0
	v_fma_f32 v128, -v117, v119, 1.0
	v_fmac_f32_e32 v119, v128, v119
	v_div_scale_f32 v128, vcc, 1.0, v127, 1.0
	v_mul_f32_e32 v129, v128, v119
	v_fma_f32 v130, -v117, v129, v128
	v_fmac_f32_e32 v129, v130, v119
	v_fma_f32 v117, -v117, v129, v128
	v_div_fmas_f32 v117, v117, v119, v129
	v_div_fixup_f32 v127, v117, v127, 1.0
	v_div_scale_f32 v117, s[0:1], v126, v126, 1.0
	v_rcp_f32_e32 v119, v117
	s_nop 0
	v_fma_f32 v128, -v117, v119, 1.0
	v_fmac_f32_e32 v119, v128, v119
	v_div_scale_f32 v128, vcc, 1.0, v126, 1.0
	v_mul_f32_e32 v129, v128, v119
	v_fma_f32 v130, -v117, v129, v128
	v_fmac_f32_e32 v129, v130, v119
	v_fma_f32 v117, -v117, v129, v128
	v_div_fmas_f32 v117, v117, v119, v129
	v_pk_mul_f32 v[128:129], v[4:5], v[66:67]
	v_div_fixup_f32 v126, v117, v126, 1.0
	v_pk_fma_f32 v[76:77], v[12:13], v[76:77], v[128:129]
	v_and_b32_e32 v117, 0xffff0000, v116
	v_lshlrev_b32_e32 v116, 16, v116
	v_pk_fma_f32 v[76:77], v[8:9], v[74:75], v[76:77]
	v_pk_mul_f32 v[68:69], v[68:69], v[126:127]
	v_pk_fma_f32 v[76:77], v[36:37], v[116:117], v[76:77]
	v_pk_mul_f32 v[126:127], v[68:69], v[68:69]
	v_mul_f32_e32 v119, 0xbfb8aa3b, v76
	v_exp_f32_e32 v128, v119
	v_mul_f32_e32 v119, 0xbfb8aa3b, v77
	v_exp_f32_e32 v129, v119
	s_nop 0
	v_pk_add_f32 v[128:129], v[128:129], 1.0 op_sel_hi:[1,0]
	s_nop 0
	v_div_scale_f32 v119, s[0:1], v129, v129, 1.0
	v_rcp_f32_e32 v130, v119
	s_nop 0
	v_fma_f32 v131, -v119, v130, 1.0
	v_fmac_f32_e32 v130, v131, v130
	v_div_scale_f32 v131, vcc, 1.0, v129, 1.0
	v_mul_f32_e32 v132, v131, v130
	v_fma_f32 v133, -v119, v132, v131
	v_fmac_f32_e32 v132, v133, v130
	v_fma_f32 v119, -v119, v132, v131
	v_div_fmas_f32 v119, v119, v130, v132
	v_div_fixup_f32 v129, v119, v129, 1.0
	v_div_scale_f32 v119, s[0:1], v128, v128, 1.0
	v_rcp_f32_e32 v130, v119
	s_nop 0
	v_fma_f32 v131, -v119, v130, 1.0
	v_fmac_f32_e32 v130, v131, v130
	v_div_scale_f32 v131, vcc, 1.0, v128, 1.0
	v_mul_f32_e32 v132, v131, v130
	v_fma_f32 v133, -v119, v132, v131
	v_fmac_f32_e32 v132, v133, v130
	v_fma_f32 v119, -v119, v132, v131
	v_div_fmas_f32 v119, v119, v130, v132
	v_div_fixup_f32 v128, v119, v128, 1.0
	v_pk_mul_f32 v[76:77], v[76:77], v[128:129]
	v_mov_b32_e32 v131, v122
	v_pk_mul_f32 v[128:129], v[76:77], v[76:77]
	s_nop 0
	v_mov_b32_e32 v130, v128
	v_mov_b32_e32 v122, v129
	v_pk_add_f32 v[122:123], v[130:131], v[122:123]
	v_mov_b32_e32 v128, v126
	v_mov_b32_e32 v129, v72
	v_pk_add_f32 v[122:123], v[128:129], v[122:123]
	v_mov_b32_e32 v72, v127
	v_pk_add_f32 v[72:73], v[72:73], v[122:123]
	v_mov_b32_e32 v123, v3
	v_mov_b32_e32 v122, v3
	s_nop 0
	v_mov_b32_dpp v123, v73 row_ror:8 row_mask:0xf bank_mask:0xf
	v_mov_b32_dpp v122, v72 row_ror:8 row_mask:0xf bank_mask:0xf
	v_pk_add_f32 v[72:73], v[72:73], v[122:123]
	v_mov_b32_e32 v123, v3
	v_mov_b32_e32 v122, v3
	s_nop 0
	v_mov_b32_dpp v123, v73 row_ror:4 row_mask:0xf bank_mask:0xf
	v_mov_b32_dpp v122, v72 row_ror:4 row_mask:0xf bank_mask:0xf
	v_pk_add_f32 v[72:73], v[72:73], v[122:123]
	v_mov_b32_e32 v123, v3
	v_mov_b32_e32 v122, v3
	s_nop 0
	v_mov_b32_dpp v123, v73 row_ror:2 row_mask:0xf bank_mask:0xf
	v_mov_b32_dpp v122, v72 row_ror:2 row_mask:0xf bank_mask:0xf
	v_pk_add_f32 v[72:73], v[72:73], v[122:123]
	v_mov_b32_e32 v123, v3
	v_mov_b32_e32 v122, v3
	s_nop 0
	v_mov_b32_dpp v123, v73 row_ror:1 row_mask:0xf bank_mask:0xf
	v_mov_b32_dpp v122, v72 row_ror:1 row_mask:0xf bank_mask:0xf
	v_pk_add_f32 v[72:73], v[72:73], v[122:123]
	ds_bpermute_b32 v123, v81, v73
	ds_bpermute_b32 v122, v81, v72
	s_waitcnt lgkmcnt(0)
; __device__ __forceinline__ float siluf_(float x) { return x * sigmoidf_(x); }
; __device__ __forceinline__ unsigned cvt2(float lo, float hi) { f32x2 v = {lo, hi}; return __builtin_bit_cast(unsigned, __builtin_convertvector(v, bf16x2_t)); }
; template <int STRIP> __device__ __forceinline__ void ph_gdn_prep_fast(const bf16* __restrict__ proj, const float* __restrict__ small, const float* __restrict__ conv_w, const float* __restrict__ a_log, const float* __restrict__ dt_bias, ...
;     ...
;                     for (int j = 0; j < 4; ++j) { float y[4]; float ss = 0.f;
; #pragma unroll
;                         for (int e = 0; e < 4; ++e) { float v = cw[which][0][e] * xf[j][e]; v += cw[which][1][e] * xf[j + 1][e]; v += cw[which][2][e] * xf[j + 2][e]; v += cw[which][3][e] * xf[j + 3][e]; y[e] = siluf_(v); ss += y[e] * y[e]; }
;                         float r = 1.f;
;                         if (which < 2) { ss = row16_sum(ss); ss += __shfl_xor(ss, 16); r = rsqrtf(ss + NORM_EPS); if (which == 0) r *= 0.08838834764831845f; }
;                         u32x2 o; o.x = cvt2(y[0] * r, y[1] * r); o.y = cvt2(y[2] * r, y[3] * r);
;                         *(u32x2*)(L + which * (64 * GP_STR * 2) + ((4 * ts + j) * GP_STR + 4 * cg) * 2) = o; }
	v_pk_add_f32 v[72:73], v[72:73], v[122:123]
	s_nop 0
	v_pk_add_f32 v[72:73], v[72:73], s[82:83] op_sel_hi:[1,0]
	s_nop 0
	v_mul_f32_e32 v119, 0x4b800000, v73
	v_cmp_gt_f32_e64 s[0:1], s22, v73
	v_cmp_gt_f32_e32 vcc, s22, v72
	s_nop 0
	v_cndmask_b32_e64 v73, v73, v119, s[0:1]
	v_rsq_f32_e32 v73, v73
	s_nop 0
	v_mul_f32_e32 v119, 0x45800000, v73
	v_cndmask_b32_e64 v73, v73, v119, s[0:1]
	v_mul_f32_e32 v122, 0x3db504f3, v73
	v_pk_mul_f32 v[120:121], v[120:121], v[122:123] op_sel_hi:[1,0]
	v_pk_mul_f32 v[70:71], v[70:71], v[122:123] op_sel_hi:[1,0]
	v_cvt_pk_bf16_f32 v120, v120, v121
	v_cvt_pk_bf16_f32 v121, v70, v71
	v_mul_f32_e32 v70, 0x4b800000, v72
	v_cndmask_b32_e32 v70, v72, v70, vcc
	v_rsq_f32_e32 v70, v70
	s_nop 0
	v_mul_f32_e32 v71, 0x45800000, v70
	v_cndmask_b32_e32 v70, v70, v71, vcc
	v_mul_f32_e32 v70, 0x3db504f3, v70
	v_pk_mul_f32 v[72:73], v[76:77], v[70:71] op_sel_hi:[1,0]
	v_pk_mul_f32 v[68:69], v[68:69], v[70:71] op_sel_hi:[1,0]
	v_pk_mul_f32 v[70:71], v[6:7], v[64:65]
	v_cvt_pk_bf16_f32 v72, v72, v73
	v_pk_fma_f32 v[62:63], v[14:15], v[62:63], v[70:71]
	v_cvt_pk_bf16_f32 v73, v68, v69
	v_and_b32_e32 v69, 0xffff0000, v115
	v_lshlrev_b32_e32 v68, 16, v115
	v_pk_fma_f32 v[62:63], v[10:11], v[124:125], v[62:63]
	ds_write2_b64 v87, v[120:121], v[72:73] offset1:34
	v_pk_fma_f32 v[62:63], v[38:39], v[68:69], v[62:63]
	s_nop 0
	v_mul_f32_e32 v70, 0xbfb8aa3b, v62
	v_mul_f32_e32 v71, 0xbfb8aa3b, v63
	v_exp_f32_e32 v70, v70
	v_exp_f32_e32 v71, v71
	s_nop 0
	v_pk_add_f32 v[70:71], v[70:71], 1.0 op_sel_hi:[1,0]
	s_nop 0
	v_div_scale_f32 v72, s[0:1], v71, v71, 1.0
	v_rcp_f32_e32 v73, v72
	s_nop 0
	v_fma_f32 v76, -v72, v73, 1.0
	v_fmac_f32_e32 v73, v76, v73
	v_div_scale_f32 v76, vcc, 1.0, v71, 1.0
	v_mul_f32_e32 v77, v76, v73
	v_fma_f32 v115, -v72, v77, v76
	v_fmac_f32_e32 v77, v115, v73
	v_fma_f32 v72, -v72, v77, v76
	v_div_fmas_f32 v72, v72, v73, v77
	v_div_fixup_f32 v71, v72, v71, 1.0
	v_div_scale_f32 v72, s[0:1], v70, v70, 1.0
	v_rcp_f32_e32 v73, v72
	s_nop 0
	v_fma_f32 v76, -v72, v73, 1.0
	v_fmac_f32_e32 v73, v76, v73
	v_div_scale_f32 v76, vcc, 1.0, v70, 1.0
	v_mul_f32_e32 v77, v76, v73
	v_fma_f32 v115, -v72, v77, v76
	v_fmac_f32_e32 v77, v115, v73
	v_fma_f32 v72, -v72, v77, v76
	v_div_fmas_f32 v72, v72, v73, v77
	v_pk_mul_f32 v[76:77], v[4:5], v[74:75]
	v_div_fixup_f32 v70, v72, v70, 1.0
	v_pk_fma_f32 v[66:67], v[12:13], v[66:67], v[76:77]
	v_and_b32_e32 v73, 0xffff0000, v113
	v_lshlrev_b32_e32 v72, 16, v113
	v_pk_fma_f32 v[66:67], v[8:9], v[116:117], v[66:67]
	v_pk_mul_f32 v[116:117], v[4:5], v[116:117]
	v_pk_fma_f32 v[66:67], v[36:37], v[72:73], v[66:67]
	v_pk_fma_f32 v[74:75], v[12:13], v[74:75], v[116:117]
	v_mul_f32_e32 v76, 0xbfb8aa3b, v66
	v_mul_f32_e32 v77, 0xbfb8aa3b, v67
	v_exp_f32_e32 v76, v76
	v_exp_f32_e32 v77, v77
	v_pk_fma_f32 v[72:73], v[8:9], v[72:73], v[74:75]
	v_pk_mul_f32 v[62:63], v[62:63], v[70:71]
	v_pk_add_f32 v[76:77], v[76:77], 1.0 op_sel_hi:[1,0]
	s_nop 0
	v_div_scale_f32 v113, s[0:1], v77, v77, 1.0
	v_rcp_f32_e32 v115, v113
	v_pk_mul_f32 v[70:71], v[62:63], v[62:63]
	v_fma_f32 v119, -v113, v115, 1.0
	v_fmac_f32_e32 v115, v119, v115
	v_div_scale_f32 v119, vcc, 1.0, v77, 1.0
	v_mul_f32_e32 v120, v119, v115
	v_fma_f32 v121, -v113, v120, v119
	v_fmac_f32_e32 v120, v121, v115
	v_fma_f32 v113, -v113, v120, v119
	v_div_fmas_f32 v113, v113, v115, v120
	v_div_fixup_f32 v77, v113, v77, 1.0
	v_div_scale_f32 v113, s[0:1], v76, v76, 1.0
	v_rcp_f32_e32 v115, v113
	s_nop 0
	v_fma_f32 v119, -v113, v115, 1.0
	v_fmac_f32_e32 v115, v119, v115
	v_div_scale_f32 v119, vcc, 1.0, v76, 1.0
	v_mul_f32_e32 v120, v119, v115
	v_fma_f32 v121, -v113, v120, v119
	v_fmac_f32_e32 v120, v121, v115
	v_fma_f32 v113, -v113, v120, v119
	v_div_fmas_f32 v113, v113, v115, v120
	v_pk_mul_f32 v[120:121], v[6:7], v[124:125]
	v_and_b32_e32 v115, 0xffff0000, v114
	v_pk_fma_f32 v[64:65], v[14:15], v[64:65], v[120:121]
	v_lshlrev_b32_e32 v114, 16, v114
	v_pk_fma_f32 v[64:65], v[10:11], v[68:69], v[64:65]
	v_div_fixup_f32 v76, v113, v76, 1.0
	v_pk_fma_f32 v[64:65], v[38:39], v[114:115], v[64:65]
	v_pk_mul_f32 v[66:67], v[66:67], v[76:77]
	v_mul_f32_e32 v68, 0xbfb8aa3b, v64
	v_mul_f32_e32 v69, 0xbfb8aa3b, v65
	v_exp_f32_e32 v68, v68
	v_exp_f32_e32 v69, v69
	v_pk_mul_f32 v[76:77], v[66:67], v[66:67]
	v_pk_add_f32 v[68:69], v[68:69], 1.0 op_sel_hi:[1,0]
	s_nop 0
	v_div_scale_f32 v113, s[0:1], v69, v69, 1.0
	v_rcp_f32_e32 v114, v113
	s_nop 0
	v_fma_f32 v115, -v113, v114, 1.0
	v_fmac_f32_e32 v114, v115, v114
	v_div_scale_f32 v115, vcc, 1.0, v69, 1.0
	v_mul_f32_e32 v119, v115, v114
	v_fma_f32 v120, -v113, v119, v115
	v_fmac_f32_e32 v119, v120, v114
	v_fma_f32 v113, -v113, v119, v115
	v_div_fmas_f32 v113, v113, v114, v119
	v_div_fixup_f32 v69, v113, v69, 1.0
	v_div_scale_f32 v113, s[0:1], v68, v68, 1.0
	v_rcp_f32_e32 v114, v113
	s_nop 0
	v_fma_f32 v115, -v113, v114, 1.0
	v_fmac_f32_e32 v114, v115, v114
	v_div_scale_f32 v115, vcc, 1.0, v68, 1.0
	v_mul_f32_e32 v119, v115, v114
	v_fma_f32 v120, -v113, v119, v115
	v_fmac_f32_e32 v119, v120, v114
	v_fma_f32 v113, -v113, v119, v115
	v_div_fmas_f32 v113, v113, v114, v119
	v_and_b32_e32 v115, 0xffff0000, v2
	v_lshlrev_b32_e32 v114, 16, v2
	v_pk_fma_f32 v[72:73], v[36:37], v[114:115], v[72:73]
	v_div_fixup_f32 v68, v113, v68, 1.0
	v_mul_f32_e32 v2, 0xbfb8aa3b, v72
	v_exp_f32_e32 v74, v2
	v_mul_f32_e32 v2, 0xbfb8aa3b, v73
	v_exp_f32_e32 v75, v2
	v_pk_mul_f32 v[64:65], v[64:65], v[68:69]
	v_pk_add_f32 v[74:75], v[74:75], 1.0 op_sel_hi:[1,0]
	s_nop 0
	v_div_scale_f32 v2, s[0:1], v75, v75, 1.0
	v_rcp_f32_e32 v113, v2
	v_pk_mul_f32 v[68:69], v[64:65], v[64:65]
	v_fma_f32 v114, -v2, v113, 1.0
	v_fmac_f32_e32 v113, v114, v113
; __device__ __forceinline__ float siluf_(float x) { return x * sigmoidf_(x); }
; __device__ __forceinline__ unsigned cvt2(float lo, float hi) { f32x2 v = {lo, hi}; return __builtin_bit_cast(unsigned, __builtin_convertvector(v, bf16x2_t)); }
; template <int STRIP> __device__ __forceinline__ void ph_gdn_prep_fast(const bf16* __restrict__ proj, const float* __restrict__ small, const float* __restrict__ conv_w, const float* __restrict__ a_log, const float* __restrict__ dt_bias, ...
;     ...
;                         for (int e = 0; e < 4; ++e) { float v = cw[which][0][e] * xf[j][e]; v += cw[which][1][e] * xf[j + 1][e]; v += cw[which][2][e] * xf[j + 2][e]; v += cw[which][3][e] * xf[j + 3][e]; y[e] = siluf_(v); ss += y[e] * y[e]; }
;                         float r = 1.f;
;                         if (which < 2) { ss = row16_sum(ss); ss += __shfl_xor(ss, 16); r = rsqrtf(ss + NORM_EPS); if (which == 0) r *= 0.08838834764831845f; }
;                         u32x2 o; o.x = cvt2(y[0] * r, y[1] * r); o.y = cvt2(y[2] * r, y[3] * r);
;                         *(u32x2*)(L + which * (64 * GP_STR * 2) + ((4 * ts + j) * GP_STR + 4 * cg) * 2) = o; }
	v_div_scale_f32 v114, vcc, 1.0, v75, 1.0
	v_mul_f32_e32 v115, v114, v113
	v_fma_f32 v116, -v2, v115, v114
	v_fmac_f32_e32 v115, v116, v113
	v_fma_f32 v2, -v2, v115, v114
	v_div_fmas_f32 v2, v2, v113, v115
	v_div_fixup_f32 v75, v2, v75, 1.0
	v_div_scale_f32 v2, s[0:1], v74, v74, 1.0
	v_rcp_f32_e32 v113, v2
	s_nop 0
	v_fma_f32 v114, -v2, v113, 1.0
	v_fmac_f32_e32 v113, v114, v113
	v_div_scale_f32 v114, vcc, 1.0, v74, 1.0
	v_mul_f32_e32 v115, v114, v113
	v_fma_f32 v116, -v2, v115, v114
	v_fmac_f32_e32 v115, v116, v113
	v_fma_f32 v2, -v2, v115, v114
	v_div_fmas_f32 v2, v2, v113, v115
	v_div_fixup_f32 v74, v2, v74, 1.0
	v_pk_mul_f32 v[72:73], v[72:73], v[74:75]
	v_mov_b32_e32 v115, v76
	v_pk_mul_f32 v[74:75], v[72:73], v[72:73]
	s_nop 0
	v_mov_b32_e32 v114, v74
	v_mov_b32_e32 v76, v75
	v_pk_add_f32 v[74:75], v[114:115], v[76:77]
	v_mov_b32_e32 v76, v68
	v_mov_b32_e32 v77, v70
	v_pk_add_f32 v[74:75], v[76:77], v[74:75]
	v_mov_b32_e32 v70, v69
	v_pk_add_f32 v[68:69], v[70:71], v[74:75]
	v_mov_b32_e32 v71, v3
	v_mov_b32_e32 v70, v3
	v_and_b32_e32 v77, 0xffff0000, v107
	v_mov_b32_dpp v71, v69 row_ror:8 row_mask:0xf bank_mask:0xf
	v_mov_b32_dpp v70, v68 row_ror:8 row_mask:0xf bank_mask:0xf
	v_pk_add_f32 v[68:69], v[68:69], v[70:71]
	v_mov_b32_e32 v71, v3
	v_mov_b32_e32 v70, v3
	s_nop 0
	v_mov_b32_dpp v71, v69 row_ror:4 row_mask:0xf bank_mask:0xf
	v_mov_b32_dpp v70, v68 row_ror:4 row_mask:0xf bank_mask:0xf
	v_pk_add_f32 v[68:69], v[68:69], v[70:71]
	v_mov_b32_e32 v71, v3
	v_mov_b32_e32 v70, v3
	s_nop 0
	v_mov_b32_dpp v71, v69 row_ror:2 row_mask:0xf bank_mask:0xf
	v_mov_b32_dpp v70, v68 row_ror:2 row_mask:0xf bank_mask:0xf
	v_pk_add_f32 v[68:69], v[68:69], v[70:71]
	v_mov_b32_e32 v71, v3
	v_mov_b32_e32 v70, v3
	s_nop 0
	v_mov_b32_dpp v71, v69 row_ror:1 row_mask:0xf bank_mask:0xf
	v_mov_b32_dpp v70, v68 row_ror:1 row_mask:0xf bank_mask:0xf
	v_pk_add_f32 v[68:69], v[68:69], v[70:71]
	ds_bpermute_b32 v71, v81, v69
	ds_bpermute_b32 v70, v81, v68
	s_waitcnt lgkmcnt(0)
	v_pk_add_f32 v[68:69], v[68:69], v[70:71]
	s_nop 0
	v_pk_add_f32 v[68:69], v[68:69], s[82:83] op_sel_hi:[1,0]
	s_nop 0
	v_mul_f32_e32 v2, 0x4b800000, v69
	v_cmp_gt_f32_e64 s[0:1], s22, v69
	v_cmp_gt_f32_e32 vcc, s22, v68
	s_nop 0
	v_cndmask_b32_e64 v2, v69, v2, s[0:1]
	v_rsq_f32_e32 v2, v2
	s_nop 0
	v_mul_f32_e32 v69, 0x45800000, v2
	v_cndmask_b32_e64 v2, v2, v69, s[0:1]
	v_mul_f32_e32 v2, 0x3db504f3, v2
	v_pk_mul_f32 v[66:67], v[66:67], v[2:3] op_sel_hi:[1,0]
	v_pk_mul_f32 v[62:63], v[62:63], v[2:3] op_sel_hi:[1,0]
	v_mul_f32_e32 v2, 0x4b800000, v68
	v_cndmask_b32_e32 v2, v68, v2, vcc
	v_rsq_f32_e32 v2, v2
	v_cvt_pk_bf16_f32 v66, v66, v67
	v_cvt_pk_bf16_f32 v67, v62, v63
	ds_write_b64 v87, v[66:67] offset:544
	v_mul_f32_e32 v62, 0x45800000, v2
	v_cndmask_b32_e32 v2, v2, v62, vcc
	v_mul_f32_e32 v2, 0x3db504f3, v2
	v_pk_mul_f32 v[62:63], v[72:73], v[2:3] op_sel_hi:[1,0]
	v_pk_mul_f32 v[64:65], v[64:65], v[2:3] op_sel_hi:[1,0]
	v_cvt_pk_bf16_f32 v62, v62, v63
	v_cvt_pk_bf16_f32 v63, v64, v65
	v_and_b32_e32 v65, 0xffff0000, v111
	v_lshlrev_b32_e32 v64, 16, v111
	v_add_u32_e32 v2, v118, v83
	v_and_b32_e32 v67, 0xffff0000, v110
	v_lshlrev_b32_e32 v66, 16, v110
	v_pk_mul_f32 v[70:71], v[30:31], v[64:65]
	ds_write_b64 v2, v[62:63]
	v_and_b32_e32 v63, 0xffff0000, v112
	v_lshlrev_b32_e32 v62, 16, v112
	v_pk_fma_f32 v[66:67], v[18:19], v[66:67], v[70:71]
	v_and_b32_e32 v69, 0xffff0000, v109
	v_lshlrev_b32_e32 v68, 16, v109
	v_pk_fma_f32 v[66:67], v[22:23], v[62:63], v[66:67]
	v_and_b32_e32 v111, 0xffff0000, v106
	v_pk_fma_f32 v[66:67], v[26:27], v[68:69], v[66:67]
	v_lshlrev_b32_e32 v110, 16, v106
	v_mul_f32_e32 v70, 0xbfb8aa3b, v66
	v_mul_f32_e32 v71, 0xbfb8aa3b, v67
	v_exp_f32_e32 v70, v70
	v_exp_f32_e32 v71, v71
	s_nop 0
	v_pk_add_f32 v[70:71], v[70:71], 1.0 op_sel_hi:[1,0]
	s_nop 0
	v_div_scale_f32 v72, s[0:1], v71, v71, 1.0
	v_rcp_f32_e32 v73, v72
	s_nop 0
	v_fma_f32 v74, -v72, v73, 1.0
	v_fmac_f32_e32 v73, v74, v73
	v_div_scale_f32 v74, vcc, 1.0, v71, 1.0
	v_mul_f32_e32 v75, v74, v73
	v_fma_f32 v76, -v72, v75, v74
	v_fmac_f32_e32 v75, v76, v73
	v_fma_f32 v72, -v72, v75, v74
	v_div_fmas_f32 v72, v72, v73, v75
	v_div_fixup_f32 v71, v72, v71, 1.0
	v_div_scale_f32 v72, s[0:1], v70, v70, 1.0
	v_rcp_f32_e32 v73, v72
	s_nop 0
	v_fma_f32 v74, -v72, v73, 1.0
	v_fmac_f32_e32 v73, v74, v73
	v_div_scale_f32 v74, vcc, 1.0, v70, 1.0
	v_mul_f32_e32 v75, v74, v73
	v_fma_f32 v76, -v72, v75, v74
	v_fmac_f32_e32 v75, v76, v73
	v_fma_f32 v72, -v72, v75, v74
	v_div_fmas_f32 v72, v72, v73, v75
	v_lshlrev_b32_e32 v76, 16, v107
	v_div_fixup_f32 v70, v72, v70, 1.0
	v_pk_mul_f32 v[106:107], v[28:29], v[76:77]
	v_pk_mul_f32 v[70:71], v[66:67], v[70:71]
	v_and_b32_e32 v67, 0xffff0000, v108
	v_lshlrev_b32_e32 v66, 16, v108
	v_pk_fma_f32 v[106:107], v[16:17], v[110:111], v[106:107]
	v_and_b32_e32 v75, 0xffff0000, v105
	v_lshlrev_b32_e32 v74, 16, v105
	v_pk_fma_f32 v[106:107], v[20:21], v[66:67], v[106:107]
	v_pk_mul_f32 v[72:73], v[70:71], v[70:71]
	v_pk_fma_f32 v[106:107], v[24:25], v[74:75], v[106:107]
	s_nop 0
	v_mul_f32_e32 v105, 0xbfb8aa3b, v106
	v_exp_f32_e32 v108, v105
	v_mul_f32_e32 v105, 0xbfb8aa3b, v107
	v_exp_f32_e32 v109, v105
	s_nop 0
	v_pk_add_f32 v[108:109], v[108:109], 1.0 op_sel_hi:[1,0]
	s_nop 0
	v_div_scale_f32 v105, s[0:1], v109, v109, 1.0
	v_rcp_f32_e32 v110, v105
	s_nop 0
	v_fma_f32 v111, -v105, v110, 1.0
	v_fmac_f32_e32 v110, v111, v110
	v_div_scale_f32 v111, vcc, 1.0, v109, 1.0
	v_mul_f32_e32 v112, v111, v110
	v_fma_f32 v113, -v105, v112, v111
	v_fmac_f32_e32 v112, v113, v110
	v_fma_f32 v105, -v105, v112, v111
	v_div_fmas_f32 v105, v105, v110, v112
	v_div_fixup_f32 v109, v105, v109, 1.0
; __device__ __forceinline__ float siluf_(float x) { return x * sigmoidf_(x); }
; template <int STRIP> __device__ __forceinline__ void ph_gdn_prep_fast(const bf16* __restrict__ proj, const float* __restrict__ small, const float* __restrict__ conv_w, const float* __restrict__ a_log, const float* __restrict__ dt_bias, ...
;     ...
;                     for (int j = 0; j < 4; ++j) { float y[4]; float ss = 0.f;
; #pragma unroll
;                         for (int e = 0; e < 4; ++e) { float v = cw[which][0][e] * xf[j][e]; v += cw[which][1][e] * xf[j + 1][e]; v += cw[which][2][e] * xf[j + 2][e]; v += cw[which][3][e] * xf[j + 3][e]; y[e] = siluf_(v); ss += y[e] * y[e]; }
;                         float r = 1.f;
;                         if (which < 2) { ss = row16_sum(ss); ss += __shfl_xor(ss, 16); r = rsqrtf(ss + NORM_EPS); if (which == 0) r *= 0.08838834764831845f; }
	v_div_scale_f32 v105, s[0:1], v108, v108, 1.0
	v_rcp_f32_e32 v110, v105
	s_nop 0
	v_fma_f32 v111, -v105, v110, 1.0
	v_fmac_f32_e32 v110, v111, v110
	v_div_scale_f32 v111, vcc, 1.0, v108, 1.0
	v_mul_f32_e32 v112, v111, v110
	v_fma_f32 v113, -v105, v112, v111
	v_fmac_f32_e32 v112, v113, v110
	v_fma_f32 v105, -v105, v112, v111
	v_div_fmas_f32 v105, v105, v110, v112
	v_pk_mul_f32 v[110:111], v[30:31], v[62:63]
	v_div_fixup_f32 v108, v105, v108, 1.0
	v_pk_fma_f32 v[64:65], v[18:19], v[64:65], v[110:111]
	v_and_b32_e32 v105, 0xffff0000, v104
	v_lshlrev_b32_e32 v104, 16, v104
	v_pk_fma_f32 v[64:65], v[22:23], v[68:69], v[64:65]
	v_pk_mul_f32 v[106:107], v[106:107], v[108:109]
	v_pk_fma_f32 v[64:65], v[26:27], v[104:105], v[64:65]
	v_pk_mul_f32 v[108:109], v[106:107], v[106:107]
	v_mul_f32_e32 v110, 0xbfb8aa3b, v64
	v_mul_f32_e32 v111, 0xbfb8aa3b, v65
	v_exp_f32_e32 v110, v110
	v_exp_f32_e32 v111, v111
	s_nop 0
	v_pk_add_f32 v[110:111], v[110:111], 1.0 op_sel_hi:[1,0]
	s_nop 0
	v_div_scale_f32 v112, s[0:1], v111, v111, 1.0
	v_rcp_f32_e32 v113, v112
	s_nop 0
	v_fma_f32 v114, -v112, v113, 1.0
	v_fmac_f32_e32 v113, v114, v113
	v_div_scale_f32 v114, vcc, 1.0, v111, 1.0
	v_mul_f32_e32 v115, v114, v113
	v_fma_f32 v116, -v112, v115, v114
	v_fmac_f32_e32 v115, v116, v113
	v_fma_f32 v112, -v112, v115, v114
	v_div_fmas_f32 v112, v112, v113, v115
	v_div_fixup_f32 v111, v112, v111, 1.0
	v_div_scale_f32 v112, s[0:1], v110, v110, 1.0
	v_rcp_f32_e32 v113, v112
	s_nop 0
	v_fma_f32 v114, -v112, v113, 1.0
	v_fmac_f32_e32 v113, v114, v113
	v_div_scale_f32 v114, vcc, 1.0, v110, 1.0
	v_mul_f32_e32 v115, v114, v113
	v_fma_f32 v116, -v112, v115, v114
	v_fmac_f32_e32 v115, v116, v113
	v_fma_f32 v112, -v112, v115, v114
	v_div_fmas_f32 v112, v112, v113, v115
	v_pk_mul_f32 v[114:115], v[28:29], v[66:67]
	v_div_fixup_f32 v110, v112, v110, 1.0
	v_pk_fma_f32 v[76:77], v[16:17], v[76:77], v[114:115]
	v_and_b32_e32 v113, 0xffff0000, v103
	v_lshlrev_b32_e32 v112, 16, v103
	v_pk_fma_f32 v[76:77], v[20:21], v[74:75], v[76:77]
	v_pk_mul_f32 v[64:65], v[64:65], v[110:111]
	v_pk_fma_f32 v[76:77], v[24:25], v[112:113], v[76:77]
	v_pk_mul_f32 v[110:111], v[64:65], v[64:65]
	v_mul_f32_e32 v103, 0xbfb8aa3b, v76
	v_exp_f32_e32 v114, v103
	v_mul_f32_e32 v103, 0xbfb8aa3b, v77
	v_exp_f32_e32 v115, v103
	s_nop 0
	v_pk_add_f32 v[114:115], v[114:115], 1.0 op_sel_hi:[1,0]
	s_nop 0
	v_div_scale_f32 v103, s[0:1], v115, v115, 1.0
	v_rcp_f32_e32 v116, v103
	s_nop 0
	v_fma_f32 v117, -v103, v116, 1.0
	v_fmac_f32_e32 v116, v117, v116
	v_div_scale_f32 v117, vcc, 1.0, v115, 1.0
	v_mul_f32_e32 v118, v117, v116
	v_fma_f32 v119, -v103, v118, v117
	v_fmac_f32_e32 v118, v119, v116
	v_fma_f32 v103, -v103, v118, v117
	v_div_fmas_f32 v103, v103, v116, v118
	v_div_fixup_f32 v115, v103, v115, 1.0
	v_div_scale_f32 v103, s[0:1], v114, v114, 1.0
	v_rcp_f32_e32 v116, v103
	s_nop 0
	v_fma_f32 v117, -v103, v116, 1.0
	v_fmac_f32_e32 v116, v117, v116
	v_div_scale_f32 v117, vcc, 1.0, v114, 1.0
	v_mul_f32_e32 v118, v117, v116
	v_fma_f32 v119, -v103, v118, v117
	v_fmac_f32_e32 v118, v119, v116
	v_fma_f32 v103, -v103, v118, v117
	v_div_fmas_f32 v103, v103, v116, v118
	v_div_fixup_f32 v114, v103, v114, 1.0
	v_pk_mul_f32 v[76:77], v[76:77], v[114:115]
	v_mov_b32_e32 v117, v108
	v_pk_mul_f32 v[114:115], v[76:77], v[76:77]
	s_nop 0
	v_mov_b32_e32 v116, v114
	v_mov_b32_e32 v108, v115
	v_pk_add_f32 v[108:109], v[116:117], v[108:109]
	v_mov_b32_e32 v114, v110
	v_mov_b32_e32 v115, v72
	v_pk_add_f32 v[108:109], v[114:115], v[108:109]
	v_mov_b32_e32 v72, v111
	v_pk_add_f32 v[72:73], v[72:73], v[108:109]
	v_mov_b32_e32 v109, v3
	v_mov_b32_e32 v108, v3
	s_nop 0
	v_mov_b32_dpp v109, v73 row_ror:8 row_mask:0xf bank_mask:0xf
	v_mov_b32_dpp v108, v72 row_ror:8 row_mask:0xf bank_mask:0xf
	v_pk_add_f32 v[72:73], v[72:73], v[108:109]
	v_mov_b32_e32 v109, v3
	v_mov_b32_e32 v108, v3
	s_nop 0
	v_mov_b32_dpp v109, v73 row_ror:4 row_mask:0xf bank_mask:0xf
	v_mov_b32_dpp v108, v72 row_ror:4 row_mask:0xf bank_mask:0xf
	v_pk_add_f32 v[72:73], v[72:73], v[108:109]
	v_mov_b32_e32 v109, v3
	v_mov_b32_e32 v108, v3
	s_nop 0
	v_mov_b32_dpp v109, v73 row_ror:2 row_mask:0xf bank_mask:0xf
	v_mov_b32_dpp v108, v72 row_ror:2 row_mask:0xf bank_mask:0xf
	v_pk_add_f32 v[72:73], v[72:73], v[108:109]
	v_mov_b32_e32 v109, v3
	v_mov_b32_e32 v108, v3
	s_nop 0
	v_mov_b32_dpp v109, v73 row_ror:1 row_mask:0xf bank_mask:0xf
	v_mov_b32_dpp v108, v72 row_ror:1 row_mask:0xf bank_mask:0xf
	v_pk_add_f32 v[72:73], v[72:73], v[108:109]
	ds_bpermute_b32 v109, v81, v73
	ds_bpermute_b32 v108, v81, v72
	s_waitcnt lgkmcnt(0)
; __device__ __forceinline__ float siluf_(float x) { return x * sigmoidf_(x); }
; __device__ __forceinline__ unsigned cvt2(float lo, float hi) { f32x2 v = {lo, hi}; return __builtin_bit_cast(unsigned, __builtin_convertvector(v, bf16x2_t)); }
; template <int STRIP> __device__ __forceinline__ void ph_gdn_prep_fast(const bf16* __restrict__ proj, const float* __restrict__ small, const float* __restrict__ conv_w, const float* __restrict__ a_log, const float* __restrict__ dt_bias, ...
;     ...
;                     for (int j = 0; j < 4; ++j) { float y[4]; float ss = 0.f;
; #pragma unroll
;                         for (int e = 0; e < 4; ++e) { float v = cw[which][0][e] * xf[j][e]; v += cw[which][1][e] * xf[j + 1][e]; v += cw[which][2][e] * xf[j + 2][e]; v += cw[which][3][e] * xf[j + 3][e]; y[e] = siluf_(v); ss += y[e] * y[e]; }
;                         float r = 1.f;
;                         if (which < 2) { ss = row16_sum(ss); ss += __shfl_xor(ss, 16); r = rsqrtf(ss + NORM_EPS); if (which == 0) r *= 0.08838834764831845f; }
;                         u32x2 o; o.x = cvt2(y[0] * r, y[1] * r); o.y = cvt2(y[2] * r, y[3] * r);
;                         *(u32x2*)(L + which * (64 * GP_STR * 2) + ((4 * ts + j) * GP_STR + 4 * cg) * 2) = o; }
	v_pk_add_f32 v[72:73], v[72:73], v[108:109]
	s_nop 0
	v_pk_add_f32 v[72:73], v[72:73], s[82:83] op_sel_hi:[1,0]
	s_nop 0
	v_mul_f32_e32 v103, 0x4b800000, v73
	v_cmp_gt_f32_e64 s[0:1], s22, v73
	v_cmp_gt_f32_e32 vcc, s22, v72
	s_nop 0
	v_cndmask_b32_e64 v73, v73, v103, s[0:1]
	v_rsq_f32_e32 v73, v73
	s_nop 0
	v_mul_f32_e32 v103, 0x45800000, v73
	v_cndmask_b32_e64 v108, v73, v103, s[0:1]
	v_pk_mul_f32 v[106:107], v[106:107], v[108:109] op_sel_hi:[1,0]
	v_pk_mul_f32 v[70:71], v[70:71], v[108:109] op_sel_hi:[1,0]
	v_cvt_pk_bf16_f32 v106, v106, v107
	v_cvt_pk_bf16_f32 v107, v70, v71
	v_mul_f32_e32 v70, 0x4b800000, v72
	v_cndmask_b32_e32 v70, v72, v70, vcc
	v_rsq_f32_e32 v70, v70
	s_nop 0
	v_mul_f32_e32 v71, 0x45800000, v70
	v_cndmask_b32_e32 v70, v70, v71, vcc
	v_pk_mul_f32 v[72:73], v[76:77], v[70:71] op_sel_hi:[1,0]
	v_pk_mul_f32 v[64:65], v[64:65], v[70:71] op_sel_hi:[1,0]
	v_pk_mul_f32 v[70:71], v[30:31], v[68:69]
	v_cvt_pk_bf16_f32 v72, v72, v73
	v_cvt_pk_bf16_f32 v73, v64, v65
	v_add_u32_e32 v64, 0x4000, v87
	v_pk_fma_f32 v[62:63], v[18:19], v[62:63], v[70:71]
	ds_write2_b64 v64, v[106:107], v[72:73] offset0:128 offset1:162
	v_and_b32_e32 v65, 0xffff0000, v102
	v_lshlrev_b32_e32 v64, 16, v102
	v_pk_fma_f32 v[62:63], v[22:23], v[104:105], v[62:63]
	s_nop 0
	v_pk_fma_f32 v[62:63], v[26:27], v[64:65], v[62:63]
	s_nop 0
	v_mul_f32_e32 v70, 0xbfb8aa3b, v62
	v_mul_f32_e32 v71, 0xbfb8aa3b, v63
	v_exp_f32_e32 v70, v70
	v_exp_f32_e32 v71, v71
	s_nop 0
	v_pk_add_f32 v[70:71], v[70:71], 1.0 op_sel_hi:[1,0]
	s_nop 0
	v_div_scale_f32 v72, s[0:1], v71, v71, 1.0
	v_rcp_f32_e32 v73, v72
	s_nop 0
	v_fma_f32 v76, -v72, v73, 1.0
	v_fmac_f32_e32 v73, v76, v73
	v_div_scale_f32 v76, vcc, 1.0, v71, 1.0
	v_mul_f32_e32 v77, v76, v73
	v_fma_f32 v102, -v72, v77, v76
	v_fmac_f32_e32 v77, v102, v73
	v_fma_f32 v72, -v72, v77, v76
	v_div_fmas_f32 v72, v72, v73, v77
	v_div_fixup_f32 v71, v72, v71, 1.0
	v_div_scale_f32 v72, s[0:1], v70, v70, 1.0
	v_rcp_f32_e32 v73, v72
	s_nop 0
	v_fma_f32 v76, -v72, v73, 1.0
	v_fmac_f32_e32 v73, v76, v73
	v_div_scale_f32 v76, vcc, 1.0, v70, 1.0
	v_mul_f32_e32 v77, v76, v73
	v_fma_f32 v102, -v72, v77, v76
	v_fmac_f32_e32 v77, v102, v73
	v_fma_f32 v72, -v72, v77, v76
	v_div_fmas_f32 v72, v72, v73, v77
	v_pk_mul_f32 v[76:77], v[28:29], v[74:75]
	v_div_fixup_f32 v70, v72, v70, 1.0
	v_pk_fma_f32 v[66:67], v[16:17], v[66:67], v[76:77]
	v_and_b32_e32 v73, 0xffff0000, v101
	v_lshlrev_b32_e32 v72, 16, v101
	v_pk_fma_f32 v[66:67], v[20:21], v[112:113], v[66:67]
	v_pk_mul_f32 v[62:63], v[62:63], v[70:71]
	v_pk_fma_f32 v[66:67], v[24:25], v[72:73], v[66:67]
	v_pk_mul_f32 v[70:71], v[62:63], v[62:63]
	v_mul_f32_e32 v76, 0xbfb8aa3b, v66
	v_mul_f32_e32 v77, 0xbfb8aa3b, v67
	v_exp_f32_e32 v76, v76
	v_exp_f32_e32 v77, v77
	s_nop 0
	v_pk_add_f32 v[76:77], v[76:77], 1.0 op_sel_hi:[1,0]
	s_nop 0
	v_div_scale_f32 v101, s[0:1], v77, v77, 1.0
	v_rcp_f32_e32 v102, v101
	s_nop 0
	v_fma_f32 v103, -v101, v102, 1.0
	v_fmac_f32_e32 v102, v103, v102
	v_div_scale_f32 v103, vcc, 1.0, v77, 1.0
	v_mul_f32_e32 v106, v103, v102
	v_fma_f32 v107, -v101, v106, v103
	v_fmac_f32_e32 v106, v107, v102
	v_fma_f32 v101, -v101, v106, v103
	v_div_fmas_f32 v101, v101, v102, v106
	v_div_fixup_f32 v77, v101, v77, 1.0
	v_div_scale_f32 v101, s[0:1], v76, v76, 1.0
	v_rcp_f32_e32 v102, v101
	s_nop 0
	v_fma_f32 v103, -v101, v102, 1.0
	v_fmac_f32_e32 v102, v103, v102
	v_div_scale_f32 v103, vcc, 1.0, v76, 1.0
	v_mul_f32_e32 v106, v103, v102
	v_fma_f32 v107, -v101, v106, v103
	v_fmac_f32_e32 v106, v107, v102
	v_fma_f32 v101, -v101, v106, v103
	v_div_fmas_f32 v101, v101, v102, v106
	v_pk_mul_f32 v[102:103], v[30:31], v[104:105]
	v_div_fixup_f32 v76, v101, v76, 1.0
	v_pk_fma_f32 v[68:69], v[18:19], v[68:69], v[102:103]
	v_and_b32_e32 v101, 0xffff0000, v100
	v_lshlrev_b32_e32 v100, 16, v100
	v_pk_fma_f32 v[64:65], v[22:23], v[64:65], v[68:69]
	v_pk_mul_f32 v[66:67], v[66:67], v[76:77]
	v_pk_fma_f32 v[64:65], v[26:27], v[100:101], v[64:65]
	v_pk_mul_f32 v[76:77], v[66:67], v[66:67]
	v_mul_f32_e32 v68, 0xbfb8aa3b, v64
	v_mul_f32_e32 v69, 0xbfb8aa3b, v65
	v_exp_f32_e32 v68, v68
	v_exp_f32_e32 v69, v69
	s_nop 0
	v_pk_add_f32 v[68:69], v[68:69], 1.0 op_sel_hi:[1,0]
	s_nop 0
	v_div_scale_f32 v100, s[0:1], v69, v69, 1.0
	v_rcp_f32_e32 v101, v100
	s_nop 0
	v_fma_f32 v102, -v100, v101, 1.0
	v_fmac_f32_e32 v101, v102, v101
	v_div_scale_f32 v102, vcc, 1.0, v69, 1.0
	v_mul_f32_e32 v103, v102, v101
	v_fma_f32 v104, -v100, v103, v102
	v_fmac_f32_e32 v103, v104, v101
	v_fma_f32 v100, -v100, v103, v102
	v_div_fmas_f32 v100, v100, v101, v103
	v_div_fixup_f32 v69, v100, v69, 1.0
	v_div_scale_f32 v100, s[0:1], v68, v68, 1.0
	v_rcp_f32_e32 v101, v100
	s_nop 0
	v_fma_f32 v102, -v100, v101, 1.0
	v_fmac_f32_e32 v101, v102, v101
	v_div_scale_f32 v102, vcc, 1.0, v68, 1.0
	v_mul_f32_e32 v103, v102, v101
	v_fma_f32 v104, -v100, v103, v102
	v_fmac_f32_e32 v103, v104, v101
	v_fma_f32 v100, -v100, v103, v102
	v_div_fmas_f32 v100, v100, v101, v103
	v_pk_mul_f32 v[102:103], v[28:29], v[112:113]
	v_div_fixup_f32 v68, v100, v68, 1.0
	v_pk_fma_f32 v[74:75], v[16:17], v[74:75], v[102:103]
	v_and_b32_e32 v101, 0xffff0000, v99
	v_lshlrev_b32_e32 v100, 16, v99
	v_pk_fma_f32 v[72:73], v[20:21], v[72:73], v[74:75]
	v_pk_mul_f32 v[64:65], v[64:65], v[68:69]
	v_pk_fma_f32 v[72:73], v[24:25], v[100:101], v[72:73]
	v_pk_mul_f32 v[68:69], v[64:65], v[64:65]
	v_mul_f32_e32 v74, 0xbfb8aa3b, v72
	v_mul_f32_e32 v75, 0xbfb8aa3b, v73
	v_exp_f32_e32 v74, v74
	v_exp_f32_e32 v75, v75
	s_nop 0
	v_pk_add_f32 v[74:75], v[74:75], 1.0 op_sel_hi:[1,0]
	s_nop 0
	v_div_scale_f32 v99, s[0:1], v75, v75, 1.0
	v_rcp_f32_e32 v100, v99
	s_nop 0
; __device__ __forceinline__ float siluf_(float x) { return x * sigmoidf_(x); }
; __device__ __forceinline__ unsigned cvt2(float lo, float hi) { f32x2 v = {lo, hi}; return __builtin_bit_cast(unsigned, __builtin_convertvector(v, bf16x2_t)); }
; template <int STRIP> __device__ __forceinline__ void ph_gdn_prep_fast(const bf16* __restrict__ proj, const float* __restrict__ small, const float* __restrict__ conv_w, const float* __restrict__ a_log, const float* __restrict__ dt_bias, ...
;     ...
;                     for (int j = 0; j < 4; ++j) { float y[4]; float ss = 0.f;
; #pragma unroll
;                         for (int e = 0; e < 4; ++e) { float v = cw[which][0][e] * xf[j][e]; v += cw[which][1][e] * xf[j + 1][e]; v += cw[which][2][e] * xf[j + 2][e]; v += cw[which][3][e] * xf[j + 3][e]; y[e] = siluf_(v); ss += y[e] * y[e]; }
;                         float r = 1.f;
;                         if (which < 2) { ss = row16_sum(ss); ss += __shfl_xor(ss, 16); r = rsqrtf(ss + NORM_EPS); if (which == 0) r *= 0.08838834764831845f; }
;                         u32x2 o; o.x = cvt2(y[0] * r, y[1] * r); o.y = cvt2(y[2] * r, y[3] * r);
;                         *(u32x2*)(L + which * (64 * GP_STR * 2) + ((4 * ts + j) * GP_STR + 4 * cg) * 2) = o; }
	v_fma_f32 v101, -v99, v100, 1.0
	v_fmac_f32_e32 v100, v101, v100
	v_div_scale_f32 v101, vcc, 1.0, v75, 1.0
	v_mul_f32_e32 v102, v101, v100
	v_fma_f32 v103, -v99, v102, v101
	v_fmac_f32_e32 v102, v103, v100
	v_fma_f32 v99, -v99, v102, v101
	v_div_fmas_f32 v99, v99, v100, v102
	v_div_fixup_f32 v75, v99, v75, 1.0
	v_div_scale_f32 v99, s[0:1], v74, v74, 1.0
	v_rcp_f32_e32 v100, v99
	s_nop 0
	v_fma_f32 v101, -v99, v100, 1.0
	v_fmac_f32_e32 v100, v101, v100
	v_div_scale_f32 v101, vcc, 1.0, v74, 1.0
	v_mul_f32_e32 v102, v101, v100
	v_fma_f32 v103, -v99, v102, v101
	v_fmac_f32_e32 v102, v103, v100
	v_fma_f32 v99, -v99, v102, v101
	v_div_fmas_f32 v99, v99, v100, v102
	v_div_fixup_f32 v74, v99, v74, 1.0
	v_pk_mul_f32 v[72:73], v[72:73], v[74:75]
	v_mov_b32_e32 v101, v76
	v_pk_mul_f32 v[74:75], v[72:73], v[72:73]
	s_nop 0
	v_mov_b32_e32 v100, v74
	v_mov_b32_e32 v76, v75
	v_pk_add_f32 v[74:75], v[100:101], v[76:77]
	v_mov_b32_e32 v76, v68
	v_mov_b32_e32 v77, v70
	v_pk_add_f32 v[74:75], v[76:77], v[74:75]
	v_mov_b32_e32 v70, v69
	v_pk_add_f32 v[68:69], v[70:71], v[74:75]
	v_mov_b32_e32 v71, v3
	v_mov_b32_e32 v70, v3
	v_and_b32_e32 v77, 0xffff0000, v94
	v_mov_b32_dpp v71, v69 row_ror:8 row_mask:0xf bank_mask:0xf
	v_mov_b32_dpp v70, v68 row_ror:8 row_mask:0xf bank_mask:0xf
	v_pk_add_f32 v[68:69], v[68:69], v[70:71]
	v_mov_b32_e32 v71, v3
	v_mov_b32_e32 v70, v3
	s_nop 0
	v_mov_b32_dpp v71, v69 row_ror:4 row_mask:0xf bank_mask:0xf
	v_mov_b32_dpp v70, v68 row_ror:4 row_mask:0xf bank_mask:0xf
	v_pk_add_f32 v[68:69], v[68:69], v[70:71]
	v_mov_b32_e32 v71, v3
	v_mov_b32_e32 v70, v3
	s_nop 0
	v_mov_b32_dpp v71, v69 row_ror:2 row_mask:0xf bank_mask:0xf
	v_mov_b32_dpp v70, v68 row_ror:2 row_mask:0xf bank_mask:0xf
	v_pk_add_f32 v[68:69], v[68:69], v[70:71]
	v_mov_b32_e32 v71, v3
	v_mov_b32_e32 v70, v3
	s_nop 0
	v_mov_b32_dpp v71, v69 row_ror:1 row_mask:0xf bank_mask:0xf
	v_mov_b32_dpp v70, v68 row_ror:1 row_mask:0xf bank_mask:0xf
	v_pk_add_f32 v[68:69], v[68:69], v[70:71]
	ds_bpermute_b32 v71, v81, v69
	ds_bpermute_b32 v70, v81, v68
	s_waitcnt lgkmcnt(0)
	v_pk_add_f32 v[68:69], v[68:69], v[70:71]
	s_nop 0
	v_pk_add_f32 v[68:69], v[68:69], s[82:83] op_sel_hi:[1,0]
	s_nop 0
	v_mul_f32_e32 v70, 0x4b800000, v69
	v_cmp_gt_f32_e64 s[0:1], s22, v69
	v_cmp_gt_f32_e32 vcc, s22, v68
	s_nop 0
	v_cndmask_b32_e64 v69, v69, v70, s[0:1]
	v_rsq_f32_e32 v69, v69
	s_nop 0
	v_mul_f32_e32 v70, 0x45800000, v69
	v_cndmask_b32_e64 v70, v69, v70, s[0:1]
	v_pk_mul_f32 v[66:67], v[66:67], v[70:71] op_sel_hi:[1,0]
	v_pk_mul_f32 v[62:63], v[62:63], v[70:71] op_sel_hi:[1,0]
	v_cvt_pk_bf16_f32 v66, v66, v67
	v_cvt_pk_bf16_f32 v67, v62, v63
	v_mul_f32_e32 v62, 0x4b800000, v68
	v_cndmask_b32_e32 v62, v68, v62, vcc
	v_rsq_f32_e32 v62, v62
	ds_write_b64 v87, v[66:67] offset:17952
	v_and_b32_e32 v69, 0xffff0000, v97
	v_lshlrev_b32_e32 v68, 16, v97
	v_mul_f32_e32 v63, 0x45800000, v62
	v_cndmask_b32_e32 v62, v62, v63, vcc
	v_pk_mul_f32 v[66:67], v[72:73], v[62:63] op_sel_hi:[1,0]
	v_pk_mul_f32 v[62:63], v[64:65], v[62:63] op_sel_hi:[1,0]
	v_cvt_pk_bf16_f32 v66, v66, v67
	v_cvt_pk_bf16_f32 v67, v62, v63
	ds_write_b64 v2, v[66:67] offset:17408
	v_and_b32_e32 v67, 0xffff0000, v96
	v_lshlrev_b32_e32 v66, 16, v96
	v_and_b32_e32 v65, 0xffff0000, v95
	v_lshlrev_b32_e32 v64, 16, v95
	v_pk_mul_f32 v[70:71], v[34:35], v[66:67]
	v_and_b32_e32 v63, 0xffff0000, v98
	v_lshlrev_b32_e32 v62, 16, v98
	v_pk_fma_f32 v[64:65], v[46:47], v[64:65], v[70:71]
	s_nop 0
	v_pk_fma_f32 v[64:65], v[42:43], v[62:63], v[64:65]
	s_nop 0
	v_pk_fma_f32 v[64:65], v[50:51], v[68:69], v[64:65]
	s_nop 0
	v_mul_f32_e32 v70, 0xbfb8aa3b, v65
	v_exp_f32_e32 v71, v70
	v_mul_f32_e32 v70, 0xbfb8aa3b, v64
	v_exp_f32_e32 v70, v70
	s_nop 0
	v_pk_add_f32 v[70:71], v[70:71], 1.0 op_sel_hi:[1,0]
	s_nop 0
	v_div_scale_f32 v72, s[0:1], v71, v71, 1.0
	v_rcp_f32_e32 v73, v72
	s_nop 0
	v_fma_f32 v74, -v72, v73, 1.0
	v_fmac_f32_e32 v73, v74, v73
	v_div_scale_f32 v74, vcc, 1.0, v71, 1.0
	v_mul_f32_e32 v75, v74, v73
	v_fma_f32 v76, -v72, v75, v74
	v_fmac_f32_e32 v75, v76, v73
	v_fma_f32 v72, -v72, v75, v74
	v_div_fmas_f32 v72, v72, v73, v75
	v_div_fixup_f32 v71, v72, v71, 1.0
	v_div_scale_f32 v72, s[0:1], v70, v70, 1.0
	v_rcp_f32_e32 v73, v72
	s_nop 0
	v_fma_f32 v74, -v72, v73, 1.0
	v_fmac_f32_e32 v73, v74, v73
	v_div_scale_f32 v74, vcc, 1.0, v70, 1.0
	v_mul_f32_e32 v75, v74, v73
	v_fma_f32 v76, -v72, v75, v74
	v_fmac_f32_e32 v75, v76, v73
	v_fma_f32 v72, -v72, v75, v74
	v_div_fmas_f32 v72, v72, v73, v75
	v_and_b32_e32 v75, 0xffff0000, v89
	v_lshlrev_b32_e32 v74, 16, v89
	v_div_fixup_f32 v70, v72, v70, 1.0
	v_and_b32_e32 v73, 0xffff0000, v88
	v_lshlrev_b32_e32 v72, 16, v88
	v_pk_mul_f32 v[88:89], v[32:33], v[74:75]
	v_lshlrev_b32_e32 v76, 16, v94
	v_pk_fma_f32 v[72:73], v[44:45], v[72:73], v[88:89]
	v_pk_mul_f32 v[70:71], v[64:65], v[70:71]
	v_and_b32_e32 v65, 0xffff0000, v91
	v_lshlrev_b32_e32 v64, 16, v91
	v_pk_fma_f32 v[72:73], v[40:41], v[76:77], v[72:73]
	s_nop 0
	v_pk_fma_f32 v[72:73], v[48:49], v[64:65], v[72:73]
	s_nop 0
	v_mul_f32_e32 v88, 0xbfb8aa3b, v73
	v_exp_f32_e32 v89, v88
	v_mul_f32_e32 v88, 0xbfb8aa3b, v72
	v_exp_f32_e32 v88, v88
	s_nop 0
	v_pk_add_f32 v[88:89], v[88:89], 1.0 op_sel_hi:[1,0]
	s_nop 0
	v_div_scale_f32 v91, s[0:1], v89, v89, 1.0
	v_rcp_f32_e32 v94, v91
	s_nop 0
	v_fma_f32 v95, -v91, v94, 1.0
	v_fmac_f32_e32 v94, v95, v94
	v_div_scale_f32 v95, vcc, 1.0, v89, 1.0
	v_mul_f32_e32 v96, v95, v94
	v_fma_f32 v97, -v91, v96, v95
	v_fmac_f32_e32 v96, v97, v94
	v_fma_f32 v91, -v91, v96, v95
	v_div_fmas_f32 v91, v91, v94, v96
	v_div_fixup_f32 v89, v91, v89, 1.0
	v_div_scale_f32 v91, s[0:1], v88, v88, 1.0
	v_rcp_f32_e32 v94, v91
; __device__ __forceinline__ float siluf_(float x) { return x * sigmoidf_(x); }
; __device__ __forceinline__ unsigned cvt2(float lo, float hi) { f32x2 v = {lo, hi}; return __builtin_bit_cast(unsigned, __builtin_convertvector(v, bf16x2_t)); }
; template <int STRIP> __device__ __forceinline__ void ph_gdn_prep_fast(const bf16* __restrict__ proj, const float* __restrict__ small, const float* __restrict__ conv_w, const float* __restrict__ a_log, const float* __restrict__ dt_bias, ...
;     ...
;                     for (int j = 0; j < 4; ++j) { float y[4]; float ss = 0.f;
; #pragma unroll
;                         for (int e = 0; e < 4; ++e) { float v = cw[which][0][e] * xf[j][e]; v += cw[which][1][e] * xf[j + 1][e]; v += cw[which][2][e] * xf[j + 2][e]; v += cw[which][3][e] * xf[j + 3][e]; y[e] = siluf_(v); ss += y[e] * y[e]; }
;                         float r = 1.f;
;                         if (which < 2) { ss = row16_sum(ss); ss += __shfl_xor(ss, 16); r = rsqrtf(ss + NORM_EPS); if (which == 0) r *= 0.08838834764831845f; }
;                         u32x2 o; o.x = cvt2(y[0] * r, y[1] * r); o.y = cvt2(y[2] * r, y[3] * r);
;                         *(u32x2*)(L + which * (64 * GP_STR * 2) + ((4 * ts + j) * GP_STR + 4 * cg) * 2) = o; }
	s_nop 0
	v_fma_f32 v95, -v91, v94, 1.0
	v_fmac_f32_e32 v94, v95, v94
	v_div_scale_f32 v95, vcc, 1.0, v88, 1.0
	v_mul_f32_e32 v96, v95, v94
	v_fma_f32 v97, -v91, v96, v95
	v_fmac_f32_e32 v96, v97, v94
	v_fma_f32 v91, -v91, v96, v95
	v_div_fmas_f32 v91, v91, v94, v96
	v_div_fixup_f32 v88, v91, v88, 1.0
	v_pk_mul_f32 v[72:73], v[72:73], v[88:89]
	v_pk_mul_f32 v[88:89], v[34:35], v[62:63]
	v_cvt_pk_bf16_f32 v72, v72, v73
	v_pk_fma_f32 v[66:67], v[46:47], v[66:67], v[88:89]
	v_cvt_pk_bf16_f32 v73, v70, v71
	v_and_b32_e32 v71, 0xffff0000, v93
	v_lshlrev_b32_e32 v70, 16, v93
	v_pk_fma_f32 v[66:67], v[42:43], v[68:69], v[66:67]
	s_nop 0
	v_pk_fma_f32 v[66:67], v[50:51], v[70:71], v[66:67]
	s_nop 0
	v_mul_f32_e32 v88, 0xbfb8aa3b, v67
	v_exp_f32_e32 v89, v88
	v_mul_f32_e32 v88, 0xbfb8aa3b, v66
	v_exp_f32_e32 v88, v88
	s_nop 0
	v_pk_add_f32 v[88:89], v[88:89], 1.0 op_sel_hi:[1,0]
	s_nop 0
	v_div_scale_f32 v91, s[0:1], v89, v89, 1.0
	v_rcp_f32_e32 v93, v91
	s_nop 0
	v_fma_f32 v94, -v91, v93, 1.0
	v_fmac_f32_e32 v93, v94, v93
	v_div_scale_f32 v94, vcc, 1.0, v89, 1.0
	v_mul_f32_e32 v95, v94, v93
	v_fma_f32 v96, -v91, v95, v94
	v_fmac_f32_e32 v95, v96, v93
	v_fma_f32 v91, -v91, v95, v94
	v_div_fmas_f32 v91, v91, v93, v95
	v_div_fixup_f32 v89, v91, v89, 1.0
	v_div_scale_f32 v91, s[0:1], v88, v88, 1.0
	v_rcp_f32_e32 v93, v91
	s_nop 0
	v_fma_f32 v94, -v91, v93, 1.0
	v_fmac_f32_e32 v93, v94, v93
	v_div_scale_f32 v94, vcc, 1.0, v88, 1.0
	v_mul_f32_e32 v95, v94, v93
	v_fma_f32 v96, -v91, v95, v94
	v_fmac_f32_e32 v95, v96, v93
	v_fma_f32 v91, -v91, v95, v94
	v_div_fmas_f32 v91, v91, v93, v95
	v_div_fixup_f32 v88, v91, v88, 1.0
	v_pk_mul_f32 v[88:89], v[66:67], v[88:89]
	v_and_b32_e32 v67, 0xffff0000, v92
	v_lshlrev_b32_e32 v66, 16, v92
	v_pk_mul_f32 v[92:93], v[32:33], v[76:77]
	s_nop 0
	v_pk_fma_f32 v[74:75], v[44:45], v[74:75], v[92:93]
	s_nop 0
	v_pk_fma_f32 v[74:75], v[40:41], v[64:65], v[74:75]
	s_nop 0
	v_pk_fma_f32 v[74:75], v[48:49], v[66:67], v[74:75]
	s_nop 0
	v_mul_f32_e32 v91, 0xbfb8aa3b, v75
	v_exp_f32_e32 v93, v91
	v_mul_f32_e32 v91, 0xbfb8aa3b, v74
	v_exp_f32_e32 v92, v91
	s_nop 0
	v_pk_add_f32 v[92:93], v[92:93], 1.0 op_sel_hi:[1,0]
	s_nop 0
	v_div_scale_f32 v91, s[0:1], v93, v93, 1.0
	v_rcp_f32_e32 v94, v91
	s_nop 0
	v_fma_f32 v95, -v91, v94, 1.0
	v_fmac_f32_e32 v94, v95, v94
	v_div_scale_f32 v95, vcc, 1.0, v93, 1.0
	v_mul_f32_e32 v96, v95, v94
	v_fma_f32 v97, -v91, v96, v95
	v_fmac_f32_e32 v96, v97, v94
	v_fma_f32 v91, -v91, v96, v95
	v_div_fmas_f32 v91, v91, v94, v96
	v_div_fixup_f32 v93, v91, v93, 1.0
	v_div_scale_f32 v91, s[0:1], v92, v92, 1.0
	v_rcp_f32_e32 v94, v91
	s_nop 0
	v_fma_f32 v95, -v91, v94, 1.0
	v_fmac_f32_e32 v94, v95, v94
	v_div_scale_f32 v95, vcc, 1.0, v92, 1.0
	v_mul_f32_e32 v96, v95, v94
	v_fma_f32 v97, -v91, v96, v95
	v_fmac_f32_e32 v96, v97, v94
	v_fma_f32 v91, -v91, v96, v95
	v_div_fmas_f32 v91, v91, v94, v96
	v_div_fixup_f32 v92, v91, v92, 1.0
	v_pk_mul_f32 v[74:75], v[74:75], v[92:93]
	s_nop 0
	v_cvt_pk_bf16_f32 v74, v74, v75
	v_cvt_pk_bf16_f32 v75, v88, v89
	v_add_u32_e32 v88, 0x8800, v87
	ds_write2_b64 v88, v[72:73], v[74:75] offset1:34
	v_pk_mul_f32 v[74:75], v[34:35], v[68:69]
	v_and_b32_e32 v73, 0xffff0000, v90
	v_pk_fma_f32 v[62:63], v[46:47], v[62:63], v[74:75]
	v_lshlrev_b32_e32 v72, 16, v90
	v_pk_fma_f32 v[62:63], v[42:43], v[70:71], v[62:63]
	v_pk_mul_f32 v[70:71], v[34:35], v[70:71]
	v_pk_fma_f32 v[62:63], v[50:51], v[72:73], v[62:63]
	v_pk_fma_f32 v[68:69], v[46:47], v[68:69], v[70:71]
	v_mul_f32_e32 v74, 0xbfb8aa3b, v63
	v_exp_f32_e32 v75, v74
	v_mul_f32_e32 v74, 0xbfb8aa3b, v62
	v_exp_f32_e32 v74, v74
	v_pk_fma_f32 v[68:69], v[42:43], v[72:73], v[68:69]
	v_pk_add_f32 v[74:75], v[74:75], 1.0 op_sel_hi:[1,0]
	s_nop 0
	v_div_scale_f32 v88, s[0:1], v75, v75, 1.0
	v_rcp_f32_e32 v89, v88
	s_nop 0
	v_fma_f32 v90, -v88, v89, 1.0
	v_fmac_f32_e32 v89, v90, v89
	v_div_scale_f32 v90, vcc, 1.0, v75, 1.0
	v_mul_f32_e32 v91, v90, v89
	v_fma_f32 v92, -v88, v91, v90
	v_fmac_f32_e32 v91, v92, v89
	v_fma_f32 v88, -v88, v91, v90
	v_div_fmas_f32 v88, v88, v89, v91
	v_div_fixup_f32 v75, v88, v75, 1.0
	v_div_scale_f32 v88, s[0:1], v74, v74, 1.0
	v_rcp_f32_e32 v89, v88
	s_nop 0
	v_fma_f32 v90, -v88, v89, 1.0
	v_fmac_f32_e32 v89, v90, v89
	v_div_scale_f32 v90, vcc, 1.0, v74, 1.0
	v_mul_f32_e32 v91, v90, v89
	v_fma_f32 v92, -v88, v91, v90
	v_fmac_f32_e32 v91, v92, v89
	v_fma_f32 v88, -v88, v91, v90
	v_div_fmas_f32 v88, v88, v89, v91
	v_div_fixup_f32 v74, v88, v74, 1.0
	v_pk_mul_f32 v[88:89], v[32:33], v[64:65]
	v_pk_mul_f32 v[62:63], v[62:63], v[74:75]
	v_pk_fma_f32 v[76:77], v[44:45], v[76:77], v[88:89]
	v_and_b32_e32 v75, 0xffff0000, v86
	v_lshlrev_b32_e32 v74, 16, v86
	v_pk_fma_f32 v[76:77], v[40:41], v[66:67], v[76:77]
	v_pk_mul_f32 v[66:67], v[32:33], v[66:67]
	v_pk_fma_f32 v[76:77], v[48:49], v[74:75], v[76:77]
	v_pk_fma_f32 v[64:65], v[44:45], v[64:65], v[66:67]
	v_mul_f32_e32 v86, 0xbfb8aa3b, v77
	v_exp_f32_e32 v89, v86
; __device__ __forceinline__ float sigmoidf_(float x) { return 1.0f / (1.0f + __expf(-x)); }
; __device__ __forceinline__ float siluf_(float x) { return x * sigmoidf_(x); }
; __device__ __forceinline__ float softplusf_(float x) { const float e = __expf(-fabsf(x)); const float lp = e < 0.01f ? e * (1.f - e * (0.5f - e * 0.33333334f)) : __logf(1.f + e); return fmaxf(x, 0.f) + lp; }
; __device__ __forceinline__ unsigned cvt2(float lo, float hi) { f32x2 v = {lo, hi}; return __builtin_bit_cast(unsigned, __builtin_convertvector(v, bf16x2_t)); }
; template <int STRIP> __device__ __forceinline__ void ph_gdn_prep_fast(const bf16* __restrict__ proj, const float* __restrict__ small, const float* __restrict__ conv_w, const float* __restrict__ a_log, const float* __restrict__ dt_bias, ...
;     ...
;                         for (int e = 0; e < 4; ++e) { float v = cw[which][0][e] * xf[j][e]; v += cw[which][1][e] * xf[j + 1][e]; v += cw[which][2][e] * xf[j + 2][e]; v += cw[which][3][e] * xf[j + 3][e]; y[e] = siluf_(v); ss += y[e] * y[e]; }
;                         float r = 1.f;
;                         if (which < 2) { ss = row16_sum(ss); ss += __shfl_xor(ss, 16); r = rsqrtf(ss + NORM_EPS); if (which == 0) r *= 0.08838834764831845f; }
;                         u32x2 o; o.x = cvt2(y[0] * r, y[1] * r); o.y = cvt2(y[2] * r, y[3] * r);
;                         *(u32x2*)(L + which * (64 * GP_STR * 2) + ((4 * ts + j) * GP_STR + 4 * cg) * 2) = o; }
;     ...
;         if (wave < 2) {
;             const int cs = wave, n = 2 * (pair & 31) + cs, ci = 2 * pair + cs; const size_t m = (size_t)b * SEQ + n * 64 + lane;
;             float* sgc = (float*)(lds_dyn + cs * GP_CHUNK + GP_SC);
;             const float beta = sigmoidf_(small[m * 32 + SM_BA + h]);
;             float g = -__expf(a_log[h]) * softplusf_(small[m * 32 + SM_AA + h] + dt_bias[h]);
	v_mul_f32_e32 v86, 0xbfb8aa3b, v76
	v_exp_f32_e32 v88, v86
	v_pk_fma_f32 v[64:65], v[40:41], v[74:75], v[64:65]
	v_pk_add_f32 v[88:89], v[88:89], 1.0 op_sel_hi:[1,0]
	s_nop 0
	v_div_scale_f32 v86, s[0:1], v89, v89, 1.0
	v_rcp_f32_e32 v90, v86
	s_nop 0
	v_fma_f32 v91, -v86, v90, 1.0
	v_fmac_f32_e32 v90, v91, v90
	v_div_scale_f32 v91, vcc, 1.0, v89, 1.0
	v_mul_f32_e32 v92, v91, v90
	v_fma_f32 v93, -v86, v92, v91
	v_fmac_f32_e32 v92, v93, v90
	v_fma_f32 v86, -v86, v92, v91
	v_div_fmas_f32 v86, v86, v90, v92
	v_div_fixup_f32 v89, v86, v89, 1.0
	v_div_scale_f32 v86, s[0:1], v88, v88, 1.0
	v_rcp_f32_e32 v90, v86
	s_nop 0
	v_fma_f32 v91, -v86, v90, 1.0
	v_fmac_f32_e32 v90, v91, v90
	v_div_scale_f32 v91, vcc, 1.0, v88, 1.0
	v_mul_f32_e32 v92, v91, v90
	v_fma_f32 v93, -v86, v92, v91
	v_fmac_f32_e32 v92, v93, v90
	v_fma_f32 v86, -v86, v92, v91
	v_div_fmas_f32 v86, v86, v90, v92
	v_div_fixup_f32 v88, v86, v88, 1.0
	v_pk_mul_f32 v[76:77], v[76:77], v[88:89]
	s_nop 0
	v_cvt_pk_bf16_f32 v76, v76, v77
	v_cvt_pk_bf16_f32 v77, v62, v63
	v_and_b32_e32 v63, 0xffff0000, v85
	v_lshlrev_b32_e32 v62, 16, v85
	v_pk_fma_f32 v[62:63], v[50:51], v[62:63], v[68:69]
	ds_write_b64 v87, v[76:77] offset:35360
	v_mul_f32_e32 v68, 0xbfb8aa3b, v63
	v_exp_f32_e32 v69, v68
	v_mul_f32_e32 v68, 0xbfb8aa3b, v62
	v_exp_f32_e32 v68, v68
	s_nop 0
	v_pk_add_f32 v[68:69], v[68:69], 1.0 op_sel_hi:[1,0]
	s_nop 0
	v_div_scale_f32 v70, s[0:1], v69, v69, 1.0
	v_rcp_f32_e32 v71, v70
	s_nop 0
	v_fma_f32 v72, -v70, v71, 1.0
	v_fmac_f32_e32 v71, v72, v71
	v_div_scale_f32 v72, vcc, 1.0, v69, 1.0
	v_mul_f32_e32 v73, v72, v71
	v_fma_f32 v76, -v70, v73, v72
	v_fmac_f32_e32 v73, v76, v71
	v_fma_f32 v70, -v70, v73, v72
	v_div_fmas_f32 v70, v70, v71, v73
	v_div_fixup_f32 v69, v70, v69, 1.0
	v_div_scale_f32 v70, s[0:1], v68, v68, 1.0
	v_rcp_f32_e32 v71, v70
	s_nop 0
	v_fma_f32 v72, -v70, v71, 1.0
	v_fmac_f32_e32 v71, v72, v71
	v_div_scale_f32 v72, vcc, 1.0, v68, 1.0
	v_mul_f32_e32 v73, v72, v71
	v_fma_f32 v76, -v70, v73, v72
	v_fmac_f32_e32 v73, v76, v71
	v_fma_f32 v70, -v70, v73, v72
	v_div_fmas_f32 v70, v70, v71, v73
	v_div_fixup_f32 v68, v70, v68, 1.0
	v_pk_mul_f32 v[62:63], v[62:63], v[68:69]
	v_and_b32_e32 v69, 0xffff0000, v84
	v_lshlrev_b32_e32 v68, 16, v84
	v_pk_fma_f32 v[64:65], v[48:49], v[68:69], v[64:65]
	s_nop 0
	v_mul_f32_e32 v66, 0xbfb8aa3b, v65
	v_exp_f32_e32 v67, v66
	v_mul_f32_e32 v66, 0xbfb8aa3b, v64
	v_exp_f32_e32 v66, v66
	s_nop 0
	v_pk_add_f32 v[66:67], v[66:67], 1.0 op_sel_hi:[1,0]
	s_nop 0
	v_div_scale_f32 v68, s[0:1], v67, v67, 1.0
	v_rcp_f32_e32 v69, v68
	s_nop 0
	v_fma_f32 v70, -v68, v69, 1.0
	v_fmac_f32_e32 v69, v70, v69
	v_div_scale_f32 v70, vcc, 1.0, v67, 1.0
	v_mul_f32_e32 v71, v70, v69
	v_fma_f32 v72, -v68, v71, v70
	v_fmac_f32_e32 v71, v72, v69
	v_fma_f32 v68, -v68, v71, v70
	v_div_fmas_f32 v68, v68, v69, v71
	v_div_fixup_f32 v67, v68, v67, 1.0
	v_div_scale_f32 v68, s[0:1], v66, v66, 1.0
	v_rcp_f32_e32 v69, v68
	s_mov_b64 s[0:1], 0
	v_fma_f32 v70, -v68, v69, 1.0
	v_fmac_f32_e32 v69, v70, v69
	v_div_scale_f32 v70, vcc, 1.0, v66, 1.0
	v_mul_f32_e32 v71, v70, v69
	v_fma_f32 v72, -v68, v71, v70
	v_fmac_f32_e32 v71, v72, v69
	v_fma_f32 v68, -v68, v71, v70
	v_div_fmas_f32 v68, v68, v69, v71
	v_div_fixup_f32 v66, v68, v66, 1.0
	v_pk_mul_f32 v[64:65], v[64:65], v[66:67]
	s_and_b64 vcc, exec, s[4:5]
	v_cvt_pk_bf16_f32 v64, v64, v65
	v_cvt_pk_bf16_f32 v65, v62, v63
	ds_write_b64 v2, v[64:65] offset:34816
	s_cbranch_vccz .LBB0_1256
	v_ashrrev_i32_e32 v9, 6, v78
	v_and_b32_e32 v2, 63, v78
	v_cmp_gt_i32_e32 vcc, 2, v9
	s_and_saveexec_b64 s[4:5], vcc
	s_cbranch_execz .LBB0_1264
	v_add_lshl_u32 v4, v53, v9, 6
	v_ashrrev_i32_e32 v5, 31, v4
	v_lshl_add_u64 v[4:5], v[54:55], 0, v[4:5]
	v_or_b32_e32 v4, v4, v2
	v_ashrrev_i32_e32 v53, 31, v52
	v_lshlrev_b64 v[4:5], 7, v[4:5]
	v_lshlrev_b64 v[10:11], 2, v[52:53]
	v_lshl_add_u64 v[4:5], s[94:95], 0, v[4:5]
	v_lshl_add_u64 v[6:7], s[44:45], 0, v[10:11]
	v_lshl_add_u64 v[4:5], v[4:5], 0, v[10:11]
	global_load_dword v6, v[6:7], off
	s_nop 0
	global_load_dword v8, v[4:5], off offset:24
	global_load_dword v7, v[4:5], off
	v_lshl_add_u64 v[4:5], s[62:63], 0, v[10:11]
	global_load_dword v4, v[4:5], off
	s_mov_b32 s0, 0xbfb8aa3b
	s_waitcnt vmcnt(2)
	v_add_f32_e32 v5, v8, v6
	v_mul_f32_e64 v6, |v5|, s0
	v_exp_f32_e32 v8, v6
	s_mov_b32 s0, 0x3c23d70a
	v_cmp_ngt_f32_e32 vcc, s0, v8
	s_and_saveexec_b64 s[0:1], vcc
	s_xor_b64 s[6:7], exec, s[0:1]
	s_cbranch_execz .LBB0_1260
	v_add_f32_e32 v6, 1.0, v8
	v_cmp_gt_f32_e32 vcc, s22, v6
	s_mov_b32 s0, 0x3f317217
	s_nop 0
	v_cndmask_b32_e64 v8, 0, 32, vcc
	v_ldexp_f32 v6, v6, v8
	v_log_f32_e32 v6, v6
	s_nop 0
	v_mul_f32_e32 v8, 0x3f317217, v6
	v_fma_f32 v8, v6, s0, -v8
	v_fmac_f32_e32 v8, 0x3377d1cf, v6
	s_mov_b32 s0, 0x7f800000
	v_fmac_f32_e32 v8, 0x3f317217, v6
	v_cmp_lt_f32_e64 s[0:1], |v6|, s0
	s_nop 1
	v_cndmask_b32_e64 v6, v6, v8, s[0:1]
	v_cndmask_b32_e32 v8, 0, v235, vcc
	v_sub_f32_e32 v6, v6, v8
